# P1 and P5 epilogues hand-written: LDS-bounced coalesced stores, packed f32 activation math, 4-group start stagger, relaxed first-iteration vmcnt with the As[1][1] prefetch hoisted before the stores
# speedup vs baseline: 1.0198x; 1.0092x over previous
;     __host__ __device__ void init(int M, int N, int G_, int c_) { base.init(M, N, G_, c_); }
; __global__ void __launch_bounds__(512) mk_fwd(Args a) {
;     ...
;     if (PH_MASK & 2) {
;         pg8::Gemm g{(const bf16_t*)a.out, (const bf16_t*)(ws + WS_WIN), M_TOK, NPROJ, 1024}; pg8::StaticOrder S; S.init(M_TOK, NPROJ, G, blk);
;         pg8::EpiProj E{ws};
;         for (int rep = 0; rep < REP_P1; ++rep)
;         pg8::gemm_phase<pg8::EpiProj, pg8::StaticOrder, true, true>(lds, g, S, E);
.LBB0_113:
	s_mov_b32 s101, 0
	s_bfe_u32 s98, s2, 0x20003
	s_cmp_eq_u32 s98, 0
	s_cbranch_scc1 .Lstg1_done

; #define PG8_STAGE(bufoff, gbase, voff) do { _Pragma("unroll") for (int _i = 0; _i < 2; ++_i) \
;         __builtin_amdgcn_global_load_lds((const unsigned*)((const char*)(gbase) + (voff)[_i]), (PG8_LAS unsigned*)(lds + (bufoff) + ldsw + _i * 8192), 16, 0, 0); } while (0)
; #define PG8_LDA(dst, b, h) do { _Pragma("unroll") for (int m = 0; m < 4; ++m) _Pragma("unroll") for (int k = 0; k < 2; ++k) dst[m][k] = *(const PG8_LAS bf16x8*)(lds + PG8_SA(b, h) + aoff + m * 2048 + k * 1024); } while (0)
; #define PG8_LDB(dst, b, h) do { _Pragma("unroll") for (int n = 0; n < 2; ++n) _Pragma("unroll") for (int k = 0; k < 2; ++k) dst[n][k] = *(const PG8_LAS bf16x8*)(lds + PG8_SB(b, h) + boff + n * 2048 + k * 1024); } while (0)
; #define PG8_MMA(ai, bj, At, Bt) do { __builtin_amdgcn_s_setprio(1); _Pragma("unroll") for (int m = 0; m < 4; ++m) _Pragma("unroll") for (int n = 0; n < 2; ++n) _Pragma("unroll") for (int k = 0; k < 2; ++k) \
;         acc[ai][bj][m][n] = __builtin_amdgcn_mfma_f32_16x16x32_bf16(Bt[n][k], At[m][k], acc[ai][bj][m][n], 0, 0, 0); __builtin_amdgcn_s_setprio(0); } while (0)
; #define PG8_WAIT_V(n) asm volatile("s_waitcnt vmcnt(" #n ")" ::: "memory")
; #define PG8_WAIT_L(n) asm volatile("s_waitcnt lgkmcnt(" #n ")" ::: "memory")
; #define PG8_BAR __builtin_amdgcn_s_barrier()
; #define PG8_SCHED __builtin_amdgcn_sched_barrier(0)
; template <class Epi, class Sched, bool ALIGN_EPI = false, bool SP2 = false>
; __device__ __forceinline__ void gemm_phase(PG8_LAS unsigned char* lds, const Gemm g, const Sched& S, const Epi& E) {
;     ...
;             const bool last = (t == nt - 2);
;             const char* a1 = cA + (size_t)(t + 1) * kstep;
;             const char* a2 = last ? nA : cA + (size_t)(t + 2) * kstep; const char* b2 = last ? nB : cB + (size_t)(t + 2) * kstep;
;             const char* a3 = a2 + kstep; const char* b3 = b2 + kstep;
;             if (last && has_next) S.a_ready(nxt);
;             if constexpr (SP2) {
;             PG8_LDB(B0, 0, 0); PG8_LDB(B1, 0, 1); PG8_SCHED; PG8_LDA(At, 0, 0); PG8_STAGE(PG8_SA(1, 1), a1 + hstep, voffA);
;             PG8_WAIT_V(8); PG8_WAIT_L(0); PG8_BAR; PG8_MMA(0, 0, At, B0); PG8_MMA(0, 1, At, B1); PG8_BAR; PG8_SCHED;
;             PG8_LDA(At, 0, 1); PG8_STAGE(PG8_SB(0, 0), b2, voffB); PG8_STAGE(PG8_SB(0, 1), b2 + hstep, voffB); PG8_STAGE(PG8_SA(0, 0), a2, voffA);
.LBB0_124:
	ds_read_b128 v[146:149], v157
	ds_read_b128 v[150:153], v157 offset:1024
	ds_read_b128 v[160:163], v157 offset:2048
	ds_read_b128 v[164:167], v157 offset:3072
	ds_read_b128 v[168:171], v158
	ds_read_b128 v[172:175], v158 offset:1024
	ds_read_b128 v[176:179], v158 offset:2048
	ds_read_b128 v[180:183], v158 offset:3072
	s_add_u32 s12, s78, 0xfffc0080
	s_addc_u32 s13, s79, -1
	s_cmp_eq_u32 s11, 12
	s_cselect_b32 s83, s3, s13
	s_cselect_b32 s82, s5, s12
	s_cselect_b32 s81, s7, s10
	s_cselect_b32 s80, s8, s9
	v_lshl_add_u64 v[218:219], s[78:79], 0, v[138:139]
	s_add_i32 m0, s87, 0xc000
	ds_read_b128 v[184:187], v159
	ds_read_b128 v[188:191], v159 offset:1024
	ds_read_b128 v[192:195], v159 offset:2048
	ds_read_b128 v[196:199], v159 offset:3072
	ds_read_b128 v[200:203], v159 offset:4096
	ds_read_b128 v[206:209], v159 offset:5120
	ds_read_b128 v[210:213], v159 offset:6144
	ds_read_b128 v[214:217], v159 offset:7168
	s_cmp_lg_u32 s101, 0
	s_cbranch_scc1 .Lgr_p1_alt1
	global_load_lds_dwordx4 v[218:219], off
	v_lshl_add_u64 v[218:219], s[78:79], 0, v[140:141]
	s_add_i32 m0, s87, 0xe000
	s_nop 0
	global_load_lds_dwordx4 v[218:219], off
	s_waitcnt vmcnt(8)
	s_branch .Lgr_p1_join1
.Lgr_p1_alt1:
	s_waitcnt vmcnt(24)
.Lgr_p1_join1:
	s_waitcnt lgkmcnt(0)
	s_barrier
	s_setprio 1
	s_waitcnt lgkmcnt(0)
	v_mfma_f32_16x16x32_bf16 v[124:127], v[146:149], v[184:187], v[124:127]
	v_mfma_f32_16x16x32_bf16 v[120:123], v[160:163], v[184:187], v[120:123]
	v_mfma_f32_16x16x32_bf16 v[108:111], v[146:149], v[192:195], v[108:111]
	v_mfma_f32_16x16x32_bf16 v[104:107], v[160:163], v[192:195], v[104:107]
	v_mfma_f32_16x16x32_bf16 v[92:95], v[146:149], v[200:203], v[92:95]
	v_mfma_f32_16x16x32_bf16 v[88:91], v[160:163], v[200:203], v[88:91]
	v_mfma_f32_16x16x32_bf16 v[76:79], v[146:149], v[210:213], v[76:79]
	v_mfma_f32_16x16x32_bf16 v[72:75], v[160:163], v[210:213], v[72:75]
	v_mfma_f32_16x16x32_bf16 v[124:127], v[150:153], v[188:191], v[124:127]
	v_mfma_f32_16x16x32_bf16 v[120:123], v[164:167], v[188:191], v[120:123]
	v_mfma_f32_16x16x32_bf16 v[108:111], v[150:153], v[196:199], v[108:111]
	v_mfma_f32_16x16x32_bf16 v[104:107], v[164:167], v[196:199], v[104:107]
	v_mfma_f32_16x16x32_bf16 v[92:95], v[150:153], v[206:209], v[92:95]
	v_mfma_f32_16x16x32_bf16 v[88:91], v[164:167], v[206:209], v[88:91]
	v_mfma_f32_16x16x32_bf16 v[76:79], v[150:153], v[214:217], v[76:79]
	v_mfma_f32_16x16x32_bf16 v[72:75], v[164:167], v[214:217], v[72:75]
	v_mfma_f32_16x16x32_bf16 v[116:119], v[168:171], v[184:187], v[116:119]
	v_mfma_f32_16x16x32_bf16 v[112:115], v[176:179], v[184:187], v[112:115]
	v_mfma_f32_16x16x32_bf16 v[100:103], v[168:171], v[192:195], v[100:103]
	v_mfma_f32_16x16x32_bf16 v[96:99], v[176:179], v[192:195], v[96:99]
	v_mfma_f32_16x16x32_bf16 v[84:87], v[168:171], v[200:203], v[84:87]
	v_mfma_f32_16x16x32_bf16 v[80:83], v[176:179], v[200:203], v[80:83]
	v_mfma_f32_16x16x32_bf16 v[68:71], v[168:171], v[210:213], v[68:71]
	v_mfma_f32_16x16x32_bf16 v[64:67], v[176:179], v[210:213], v[64:67]
	v_mfma_f32_16x16x32_bf16 v[116:119], v[172:175], v[188:191], v[116:119]
	v_mfma_f32_16x16x32_bf16 v[112:115], v[180:183], v[188:191], v[112:115]
	v_mfma_f32_16x16x32_bf16 v[100:103], v[172:175], v[196:199], v[100:103]
	v_mfma_f32_16x16x32_bf16 v[96:99], v[180:183], v[196:199], v[96:99]
	v_mfma_f32_16x16x32_bf16 v[84:87], v[172:175], v[206:209], v[84:87]
	v_mfma_f32_16x16x32_bf16 v[80:83], v[180:183], v[206:209], v[80:83]
	v_mfma_f32_16x16x32_bf16 v[68:71], v[172:175], v[214:217], v[68:71]
	v_mfma_f32_16x16x32_bf16 v[64:67], v[180:183], v[214:217], v[64:67]
	s_setprio 0
	s_barrier
	s_add_i32 s12, s94, s86
	v_lshl_add_u64 v[218:219], s[80:81], 0, v[130:131]
	s_mov_b32 m0, s12
	ds_read_b128 v[184:187], v159 offset:16384
	ds_read_b128 v[188:191], v159 offset:17408
	ds_read_b128 v[192:195], v159 offset:18432
	ds_read_b128 v[196:199], v159 offset:19456
	ds_read_b128 v[200:203], v159 offset:20480
	ds_read_b128 v[206:209], v159 offset:21504
	ds_read_b128 v[210:213], v159 offset:22528
	ds_read_b128 v[214:217], v159 offset:23552
	global_load_lds_dwordx4 v[218:219], off
	s_add_i32 m0, s12, 0x2000
	s_add_u32 s12, s80, 0x40000
	v_lshl_add_u64 v[220:221], s[80:81], 0, v[134:135]
	s_addc_u32 s13, s81, 0
	s_add_i32 s23, s95, s86
	global_load_lds_dwordx4 v[220:221], off
	v_lshl_add_u64 v[222:223], s[12:13], 0, v[130:131]
	s_mov_b32 m0, s23
	v_lshl_add_u64 v[224:225], s[82:83], 0, v[132:133]
	global_load_lds_dwordx4 v[222:223], off
	v_lshl_add_u64 v[222:223], s[12:13], 0, v[134:135]
	s_add_i32 m0, s23, 0x2000
	s_nop 0
	global_load_lds_dwordx4 v[222:223], off
	v_lshl_add_u64 v[222:223], s[82:83], 0, v[128:129]
	s_mov_b32 m0, s87
	s_nop 0
	global_load_lds_dwordx4 v[222:223], off
	s_mov_b32 m0, s88
	s_nop 0
	global_load_lds_dwordx4 v[224:225], off
	s_waitcnt vmcnt(24)
	s_cmp_lg_u32 s101, 0
	s_cbranch_scc1 .Lgr_p1_skip2
	s_waitcnt vmcnt(8)
; #define PG8_STAGE(bufoff, gbase, voff) do { _Pragma("unroll") for (int _i = 0; _i < 2; ++_i) \
;         __builtin_amdgcn_global_load_lds((const unsigned*)((const char*)(gbase) + (voff)[_i]), (PG8_LAS unsigned*)(lds + (bufoff) + ldsw + _i * 8192), 16, 0, 0); } while (0)
; #define PG8_LDA(dst, b, h) do { _Pragma("unroll") for (int m = 0; m < 4; ++m) _Pragma("unroll") for (int k = 0; k < 2; ++k) dst[m][k] = *(const PG8_LAS bf16x8*)(lds + PG8_SA(b, h) + aoff + m * 2048 + k * 1024); } while (0)
; #define PG8_LDB(dst, b, h) do { _Pragma("unroll") for (int n = 0; n < 2; ++n) _Pragma("unroll") for (int k = 0; k < 2; ++k) dst[n][k] = *(const PG8_LAS bf16x8*)(lds + PG8_SB(b, h) + boff + n * 2048 + k * 1024); } while (0)
; #define PG8_MMA(ai, bj, At, Bt) do { __builtin_amdgcn_s_setprio(1); _Pragma("unroll") for (int m = 0; m < 4; ++m) _Pragma("unroll") for (int n = 0; n < 2; ++n) _Pragma("unroll") for (int k = 0; k < 2; ++k) \
;         acc[ai][bj][m][n] = __builtin_amdgcn_mfma_f32_16x16x32_bf16(Bt[n][k], At[m][k], acc[ai][bj][m][n], 0, 0, 0); __builtin_amdgcn_s_setprio(0); } while (0)
; #define PG8_WAIT_V(n) asm volatile("s_waitcnt vmcnt(" #n ")" ::: "memory")
; #define PG8_WAIT_L(n) asm volatile("s_waitcnt lgkmcnt(" #n ")" ::: "memory")
; #define PG8_BAR __builtin_amdgcn_s_barrier()
; #define PG8_SCHED __builtin_amdgcn_sched_barrier(0)
; template <class Epi, class Sched, bool ALIGN_EPI = false, bool SP2 = false>
; __device__ __forceinline__ void gemm_phase(PG8_LAS unsigned char* lds, const Gemm g, const Sched& S, const Epi& E) {
;     ...
;             PG8_WAIT_V(8); PG8_WAIT_L(0); PG8_BAR; PG8_MMA(1, 0, At, B0); PG8_MMA(1, 1, At, B1); PG8_BAR; PG8_SCHED;
;             PG8_LDB(B0, 1, 0); PG8_LDB(B1, 1, 1); PG8_SCHED; PG8_LDA(At, 1, 0); PG8_STAGE(PG8_SA(0, 1), a2 + hstep, voffA);
;             PG8_WAIT_V(8); PG8_WAIT_L(0); PG8_BAR; PG8_MMA(0, 0, At, B0); PG8_MMA(0, 1, At, B1); PG8_BAR; PG8_SCHED;
.Lgr_p1_skip2:
	s_waitcnt lgkmcnt(0)
	s_barrier
	s_setprio 1
	s_waitcnt lgkmcnt(0)
	v_mfma_f32_16x16x32_bf16 v[60:63], v[146:149], v[184:187], v[60:63]
	v_mfma_f32_16x16x32_bf16 v[56:59], v[160:163], v[184:187], v[56:59]
	v_mfma_f32_16x16x32_bf16 v[44:47], v[146:149], v[192:195], v[44:47]
	v_mfma_f32_16x16x32_bf16 v[40:43], v[160:163], v[192:195], v[40:43]
	v_mfma_f32_16x16x32_bf16 v[28:31], v[146:149], v[200:203], v[28:31]
	v_mfma_f32_16x16x32_bf16 v[24:27], v[160:163], v[200:203], v[24:27]
	v_mfma_f32_16x16x32_bf16 v[12:15], v[146:149], v[210:213], v[12:15]
	v_mfma_f32_16x16x32_bf16 v[8:11], v[160:163], v[210:213], v[8:11]
	v_mfma_f32_16x16x32_bf16 v[60:63], v[150:153], v[188:191], v[60:63]
	v_mfma_f32_16x16x32_bf16 v[56:59], v[164:167], v[188:191], v[56:59]
	v_mfma_f32_16x16x32_bf16 v[44:47], v[150:153], v[196:199], v[44:47]
	v_mfma_f32_16x16x32_bf16 v[40:43], v[164:167], v[196:199], v[40:43]
	v_mfma_f32_16x16x32_bf16 v[28:31], v[150:153], v[206:209], v[28:31]
	v_mfma_f32_16x16x32_bf16 v[24:27], v[164:167], v[206:209], v[24:27]
	v_mfma_f32_16x16x32_bf16 v[12:15], v[150:153], v[214:217], v[12:15]
	v_mfma_f32_16x16x32_bf16 v[8:11], v[164:167], v[214:217], v[8:11]
	v_mfma_f32_16x16x32_bf16 v[52:55], v[168:171], v[184:187], v[52:55]
	v_mfma_f32_16x16x32_bf16 v[48:51], v[176:179], v[184:187], v[48:51]
	v_mfma_f32_16x16x32_bf16 v[36:39], v[168:171], v[192:195], v[36:39]
	v_mfma_f32_16x16x32_bf16 v[32:35], v[176:179], v[192:195], v[32:35]
	v_mfma_f32_16x16x32_bf16 v[20:23], v[168:171], v[200:203], v[20:23]
	v_mfma_f32_16x16x32_bf16 v[16:19], v[176:179], v[200:203], v[16:19]
	v_mfma_f32_16x16x32_bf16 v[4:7], v[168:171], v[210:213], v[4:7]
	v_mfma_f32_16x16x32_bf16 v[0:3], v[176:179], v[210:213], v[0:3]
	v_mfma_f32_16x16x32_bf16 v[52:55], v[172:175], v[188:191], v[52:55]
	v_mfma_f32_16x16x32_bf16 v[48:51], v[180:183], v[188:191], v[48:51]
	v_mfma_f32_16x16x32_bf16 v[36:39], v[172:175], v[196:199], v[36:39]
	v_mfma_f32_16x16x32_bf16 v[32:35], v[180:183], v[196:199], v[32:35]
	v_mfma_f32_16x16x32_bf16 v[20:23], v[172:175], v[206:209], v[20:23]
	v_mfma_f32_16x16x32_bf16 v[16:19], v[180:183], v[206:209], v[16:19]
	v_mfma_f32_16x16x32_bf16 v[4:7], v[172:175], v[214:217], v[4:7]
	v_mfma_f32_16x16x32_bf16 v[0:3], v[180:183], v[214:217], v[0:3]
	s_setprio 0
	s_barrier
	s_add_i32 s23, 0, 0x18000
	v_add_u32_e32 v136, s23, v155
	s_add_i32 s25, 0, 0x1c000
	ds_read_b128 v[146:149], v136
	ds_read_b128 v[150:153], v136 offset:1024
	ds_read_b128 v[160:163], v136 offset:2048
	ds_read_b128 v[164:167], v136 offset:3072
	v_add_u32_e32 v136, s25, v155
	ds_read_b128 v[168:171], v136
	ds_read_b128 v[172:175], v136 offset:1024
	ds_read_b128 v[176:179], v136 offset:2048
	ds_read_b128 v[180:183], v136 offset:3072
	s_add_u32 s12, s82, 0x40000
	s_addc_u32 s13, s83, 0
	s_mov_b32 m0, s89
	v_lshl_add_u64 v[226:227], s[12:13], 0, v[128:129]
	ds_read_b128 v[184:187], v159 offset:32768
	ds_read_b128 v[188:191], v159 offset:33792
	ds_read_b128 v[192:195], v159 offset:34816
	ds_read_b128 v[196:199], v159 offset:35840
	ds_read_b128 v[200:203], v159 offset:36864
	ds_read_b128 v[206:209], v159 offset:37888
	ds_read_b128 v[210:213], v159 offset:38912
	ds_read_b128 v[214:217], v159 offset:39936
	global_load_lds_dwordx4 v[226:227], off
	v_lshl_add_u64 v[226:227], s[12:13], 0, v[132:133]
	s_mov_b32 m0, s90
	s_nop 0
	global_load_lds_dwordx4 v[226:227], off
	s_waitcnt vmcnt(24)
	s_cmp_lg_u32 s101, 0
	s_cbranch_scc1 .Lgr_p1_skip3
	s_waitcnt vmcnt(8)
; #define PG8_STAGE(bufoff, gbase, voff) do { _Pragma("unroll") for (int _i = 0; _i < 2; ++_i) \
;         __builtin_amdgcn_global_load_lds((const unsigned*)((const char*)(gbase) + (voff)[_i]), (PG8_LAS unsigned*)(lds + (bufoff) + ldsw + _i * 8192), 16, 0, 0); } while (0)
; #define PG8_LDA(dst, b, h) do { _Pragma("unroll") for (int m = 0; m < 4; ++m) _Pragma("unroll") for (int k = 0; k < 2; ++k) dst[m][k] = *(const PG8_LAS bf16x8*)(lds + PG8_SA(b, h) + aoff + m * 2048 + k * 1024); } while (0)
; #define PG8_MMA(ai, bj, At, Bt) do { __builtin_amdgcn_s_setprio(1); _Pragma("unroll") for (int m = 0; m < 4; ++m) _Pragma("unroll") for (int n = 0; n < 2; ++n) _Pragma("unroll") for (int k = 0; k < 2; ++k) \
;         acc[ai][bj][m][n] = __builtin_amdgcn_mfma_f32_16x16x32_bf16(Bt[n][k], At[m][k], acc[ai][bj][m][n], 0, 0, 0); __builtin_amdgcn_s_setprio(0); } while (0)
; #define PG8_WAIT_V(n) asm volatile("s_waitcnt vmcnt(" #n ")" ::: "memory")
; #define PG8_WAIT_L(n) asm volatile("s_waitcnt lgkmcnt(" #n ")" ::: "memory")
; #define PG8_BAR __builtin_amdgcn_s_barrier()
; #define PG8_SCHED __builtin_amdgcn_sched_barrier(0)
;     __device__ __forceinline__ void operator()(const f32x4 (&acc)[2][2][4][2], const Unit& u, int wr, int wc, int fr, int fq) const {
;     ...
;         if (pn < 16) { off = WS_QK + (size_t)(pn >> 2) * (64 * MiB); colt = (pn & 3) * 256; if ((pn >> 2) == 2) act = 2; }
;         else if (pn < 18) { off = WS_SKV; ldc = 512; colt = (pn - 16) * 256; }
;         else if (pn < 22) { off = WS_GA; colt = (pn - 18) * 256; act = 1; }
;         else { off = WS_GB; colt = (pn - 22) * 256; act = 1; }
; template <class Epi, class Sched, bool ALIGN_EPI = false, bool SP2 = false>
; __device__ __forceinline__ void gemm_phase(PG8_LAS unsigned char* lds, const Gemm g, const Sched& S, const Epi& E) {
;     ...
;             PG8_LDA(At, 1, 1); PG8_STAGE(PG8_SB(1, 0), b3, voffB); PG8_STAGE(PG8_SB(1, 1), b3 + hstep, voffB); PG8_STAGE(PG8_SA(1, 0), a3, voffA);
;             PG8_WAIT_V(8); PG8_WAIT_L(0); PG8_BAR; PG8_MMA(1, 0, At, B0); PG8_MMA(1, 1, At, B1); PG8_BAR; PG8_SCHED;
.Lgr_p1_skip3:
	s_waitcnt lgkmcnt(0)
	s_barrier
	s_setprio 1
	s_waitcnt lgkmcnt(0)
	v_mfma_f32_16x16x32_bf16 v[124:127], v[146:149], v[184:187], v[124:127]
	v_mfma_f32_16x16x32_bf16 v[120:123], v[160:163], v[184:187], v[120:123]
	v_mfma_f32_16x16x32_bf16 v[108:111], v[146:149], v[192:195], v[108:111]
	v_mfma_f32_16x16x32_bf16 v[104:107], v[160:163], v[192:195], v[104:107]
	v_mfma_f32_16x16x32_bf16 v[92:95], v[146:149], v[200:203], v[92:95]
	v_mfma_f32_16x16x32_bf16 v[88:91], v[160:163], v[200:203], v[88:91]
	v_mfma_f32_16x16x32_bf16 v[76:79], v[146:149], v[210:213], v[76:79]
	v_mfma_f32_16x16x32_bf16 v[72:75], v[160:163], v[210:213], v[72:75]
	v_mfma_f32_16x16x32_bf16 v[124:127], v[150:153], v[188:191], v[124:127]
	v_mfma_f32_16x16x32_bf16 v[120:123], v[164:167], v[188:191], v[120:123]
	v_mfma_f32_16x16x32_bf16 v[108:111], v[150:153], v[196:199], v[108:111]
	v_mfma_f32_16x16x32_bf16 v[104:107], v[164:167], v[196:199], v[104:107]
	v_mfma_f32_16x16x32_bf16 v[92:95], v[150:153], v[206:209], v[92:95]
	v_mfma_f32_16x16x32_bf16 v[88:91], v[164:167], v[206:209], v[88:91]
	v_mfma_f32_16x16x32_bf16 v[76:79], v[150:153], v[214:217], v[76:79]
	v_mfma_f32_16x16x32_bf16 v[72:75], v[164:167], v[214:217], v[72:75]
	v_mfma_f32_16x16x32_bf16 v[116:119], v[168:171], v[184:187], v[116:119]
	v_mfma_f32_16x16x32_bf16 v[112:115], v[176:179], v[184:187], v[112:115]
	v_mfma_f32_16x16x32_bf16 v[100:103], v[168:171], v[192:195], v[100:103]
	v_mfma_f32_16x16x32_bf16 v[96:99], v[176:179], v[192:195], v[96:99]
	v_mfma_f32_16x16x32_bf16 v[84:87], v[168:171], v[200:203], v[84:87]
	v_mfma_f32_16x16x32_bf16 v[80:83], v[176:179], v[200:203], v[80:83]
	v_mfma_f32_16x16x32_bf16 v[68:71], v[168:171], v[210:213], v[68:71]
	v_mfma_f32_16x16x32_bf16 v[64:67], v[176:179], v[210:213], v[64:67]
	v_mfma_f32_16x16x32_bf16 v[116:119], v[172:175], v[188:191], v[116:119]
	v_mfma_f32_16x16x32_bf16 v[112:115], v[180:183], v[188:191], v[112:115]
	v_mfma_f32_16x16x32_bf16 v[100:103], v[172:175], v[196:199], v[100:103]
	v_mfma_f32_16x16x32_bf16 v[96:99], v[180:183], v[196:199], v[96:99]
	v_mfma_f32_16x16x32_bf16 v[84:87], v[172:175], v[206:209], v[84:87]
	v_mfma_f32_16x16x32_bf16 v[80:83], v[180:183], v[206:209], v[80:83]
	v_mfma_f32_16x16x32_bf16 v[68:71], v[172:175], v[214:217], v[68:71]
	v_mfma_f32_16x16x32_bf16 v[64:67], v[180:183], v[214:217], v[64:67]
	s_setprio 0
	s_barrier
	s_add_i32 s12, s23, s86
	v_lshl_add_u64 v[218:219], v[218:219], 0, s[18:19]
	s_mov_b32 m0, s12
	ds_read_b128 v[184:187], v159 offset:49152
	ds_read_b128 v[188:191], v159 offset:50176
	ds_read_b128 v[192:195], v159 offset:51200
	ds_read_b128 v[196:199], v159 offset:52224
	ds_read_b128 v[200:203], v159 offset:53248
	ds_read_b128 v[206:209], v159 offset:54272
	ds_read_b128 v[210:213], v159 offset:55296
	ds_read_b128 v[214:217], v159 offset:56320
	global_load_lds_dwordx4 v[218:219], off
	s_add_i32 m0, s12, 0x2000
	s_add_u32 s12, s80, 0x40080
	v_lshl_add_u64 v[218:219], v[220:221], 0, s[18:19]
	s_addc_u32 s13, s81, 0
	s_add_i32 s23, s25, s86
	global_load_lds_dwordx4 v[218:219], off
	v_lshl_add_u64 v[218:219], s[12:13], 0, v[130:131]
	s_mov_b32 m0, s23
	s_nop 0
	global_load_lds_dwordx4 v[218:219], off
	v_lshl_add_u64 v[218:219], s[12:13], 0, v[134:135]
	s_add_i32 m0, s23, 0x2000
	s_nop 0
	global_load_lds_dwordx4 v[218:219], off
	v_lshl_add_u64 v[218:219], v[222:223], 0, s[18:19]
	s_mov_b32 m0, s92
	s_nop 0
	global_load_lds_dwordx4 v[218:219], off
	v_lshl_add_u64 v[218:219], v[224:225], 0, s[18:19]
	s_mov_b32 m0, s93
	s_nop 0
	global_load_lds_dwordx4 v[218:219], off
	s_waitcnt vmcnt(8)
	s_waitcnt lgkmcnt(0)
	s_barrier
	s_setprio 1
	s_waitcnt lgkmcnt(0)
	v_mfma_f32_16x16x32_bf16 v[60:63], v[146:149], v[184:187], v[60:63]
	v_mfma_f32_16x16x32_bf16 v[56:59], v[160:163], v[184:187], v[56:59]
	v_mfma_f32_16x16x32_bf16 v[44:47], v[146:149], v[192:195], v[44:47]
	v_mfma_f32_16x16x32_bf16 v[40:43], v[160:163], v[192:195], v[40:43]
	v_mfma_f32_16x16x32_bf16 v[28:31], v[146:149], v[200:203], v[28:31]
	v_mfma_f32_16x16x32_bf16 v[24:27], v[160:163], v[200:203], v[24:27]
	v_mfma_f32_16x16x32_bf16 v[12:15], v[146:149], v[210:213], v[12:15]
	v_mfma_f32_16x16x32_bf16 v[8:11], v[160:163], v[210:213], v[8:11]
	v_mfma_f32_16x16x32_bf16 v[60:63], v[150:153], v[188:191], v[60:63]
	v_mfma_f32_16x16x32_bf16 v[56:59], v[164:167], v[188:191], v[56:59]
	v_mfma_f32_16x16x32_bf16 v[44:47], v[150:153], v[196:199], v[44:47]
	v_mfma_f32_16x16x32_bf16 v[40:43], v[164:167], v[196:199], v[40:43]
	v_mfma_f32_16x16x32_bf16 v[28:31], v[150:153], v[206:209], v[28:31]
	v_mfma_f32_16x16x32_bf16 v[24:27], v[164:167], v[206:209], v[24:27]
	v_mfma_f32_16x16x32_bf16 v[12:15], v[150:153], v[214:217], v[12:15]
	v_mfma_f32_16x16x32_bf16 v[8:11], v[164:167], v[214:217], v[8:11]
	v_mfma_f32_16x16x32_bf16 v[52:55], v[168:171], v[184:187], v[52:55]
	v_mfma_f32_16x16x32_bf16 v[48:51], v[176:179], v[184:187], v[48:51]
	v_mfma_f32_16x16x32_bf16 v[36:39], v[168:171], v[192:195], v[36:39]
	v_mfma_f32_16x16x32_bf16 v[32:35], v[176:179], v[192:195], v[32:35]
	v_mfma_f32_16x16x32_bf16 v[20:23], v[168:171], v[200:203], v[20:23]
	v_mfma_f32_16x16x32_bf16 v[16:19], v[176:179], v[200:203], v[16:19]
	v_mfma_f32_16x16x32_bf16 v[4:7], v[168:171], v[210:213], v[4:7]
	v_mfma_f32_16x16x32_bf16 v[0:3], v[176:179], v[210:213], v[0:3]
	v_mfma_f32_16x16x32_bf16 v[52:55], v[172:175], v[188:191], v[52:55]
	v_mfma_f32_16x16x32_bf16 v[48:51], v[180:183], v[188:191], v[48:51]
	v_mfma_f32_16x16x32_bf16 v[36:39], v[172:175], v[196:199], v[36:39]
	v_mfma_f32_16x16x32_bf16 v[32:35], v[180:183], v[196:199], v[32:35]
	v_mfma_f32_16x16x32_bf16 v[20:23], v[172:175], v[206:209], v[20:23]
	v_mfma_f32_16x16x32_bf16 v[16:19], v[180:183], v[206:209], v[16:19]
	v_mfma_f32_16x16x32_bf16 v[4:7], v[172:175], v[214:217], v[4:7]
	v_mfma_f32_16x16x32_bf16 v[0:3], v[180:183], v[214:217], v[0:3]
	s_setprio 0
	s_barrier
	s_add_i32 s11, s11, 2
	s_add_u32 s78, s78, 0x100
	s_addc_u32 s79, s79, 0
	s_add_u32 s9, s9, 0x100
	s_addc_u32 s10, s10, 0
	s_mov_b32 s101, 0
	s_cmp_gt_u32 s11, 13
	s_cbranch_scc0 .LBB0_124
	s_and_b64 vcc, exec, s[20:21]
	s_cbranch_vccz .LBB0_127
	s_barrier
.LBB0_127:
	s_add_u32 s98, s5, 0x40080
	s_addc_u32 s99, s3, 0
	v_lshl_add_u64 v[218:219], s[98:99], 0, v[138:139]
	s_add_i32 m0, s87, 0xc000
	s_nop 0
	global_load_lds_dwordx4 v[218:219], off
	v_lshl_add_u64 v[218:219], s[98:99], 0, v[140:141]
	s_add_i32 m0, s87, 0xe000
	s_nop 0
	global_load_lds_dwordx4 v[218:219], off
	s_mov_b32 s101, 1
	s_cmp_gt_i32 s4, 15
	s_mov_b64 s[8:9], -1
	s_cbranch_scc0 .LBB0_137
	s_mov_b64 s[82:83], -1
	s_cmp_gt_u32 s4, 17
	s_cbranch_scc0 .LBB0_134
	s_lshl_b32 s5, s4, 8
	s_cmp_gt_u32 s4, 21
	s_cbranch_scc0 .LBB0_131
	s_add_i32 s3, s5, 0xffffea00
	s_mov_b64 s[8:9], 0

; __device__ __forceinline__ u32x4 pack8(const float (&f)[8]) { u32x4 w; w.x = cvt_pk_bf16(f[0], f[1]); w.y = cvt_pk_bf16(f[2], f[3]); w.z = cvt_pk_bf16(f[4], f[5]); w.w = cvt_pk_bf16(f[6], f[7]); return w; }
; __device__ __forceinline__ float sigm(float x) { return __builtin_amdgcn_rcpf(1.f + __builtin_amdgcn_exp2f(-1.4426950408889634f * x)); }
;     __device__ __forceinline__ void operator()(const f32x4 (&acc)[2][2][4][2], const Unit& u, int wr, int wc, int fr, int fq) const {
;     ...
;                     if (act == 1) {
; #pragma unroll
;                         for (int e = 0; e < 8; ++e) f[e] = sigm(f[e]);
;                     } else if (act == 2) {
; #pragma unroll
;                         for (int e = 0; e < 8; ++e) f[e] = f[e] * sigm(f[e]);
;                     }
;                     __builtin_nontemporal_store(pack8(f), (u32x4*)(rowp + bj * HALF)); } }
.LBB0_139:
	s_or_b64 s[98:99], s[82:83], s[84:85]
	s_cmp_eq_u64 s[98:99], 0
	s_cbranch_scc1 .Lp1_plain
	s_cmp_eq_u64 s[82:83], 0
	s_cbranch_scc1 .Lp1_silu
	s_branch .Lp1_sig
	s_xor_b64 s[82:83], s[82:83], -1
	v_cndmask_b32_e64 v136, 0, 1, s[84:85]
	s_mov_b64 s[8:9], -1
	s_and_b64 vcc, exec, s[82:83]
	v_cmp_ne_u32_e64 s[4:5], 1, v136
	s_cbranch_vccz .LBB0_142
	s_and_b64 vcc, exec, s[4:5]
	s_cbranch_vccnz .LBB0_222
	v_mul_f32_e32 v136, 0xbfb8aa3b, v124
	v_exp_f32_e32 v136, v136
	v_mul_f32_e32 v146, 0xbfb8aa3b, v125
	v_mul_f32_e32 v147, 0xbfb8aa3b, v126
	v_exp_f32_e32 v148, v146
	v_exp_f32_e32 v149, v147
	v_add_f32_e32 v136, 1.0, v136
	v_rcp_f32_e32 v146, v136
	v_add_f32_e32 v136, 1.0, v148
	v_mul_f32_e32 v148, 0xbfb8aa3b, v127
	v_rcp_f32_e32 v147, v136
	v_add_f32_e32 v136, 1.0, v149
	v_exp_f32_e32 v149, v148
	v_mul_f32_e32 v148, 0xbfb8aa3b, v120
	v_exp_f32_e32 v150, v148
	v_rcp_f32_e32 v148, v136
	v_add_f32_e32 v136, 1.0, v149
	v_rcp_f32_e32 v149, v136
	v_add_f32_e32 v136, 1.0, v150
	v_mul_f32_e32 v151, 0xbfb8aa3b, v122
	v_rcp_f32_e32 v150, v136
	v_mul_f32_e32 v136, 0xbfb8aa3b, v121
	v_exp_f32_e32 v151, v151
	v_mul_f32_e32 v152, 0xbfb8aa3b, v123
	v_exp_f32_e32 v136, v136
	v_exp_f32_e32 v153, v152
	v_add_f32_e32 v151, 1.0, v151
	v_rcp_f32_e32 v152, v151
	v_add_f32_e32 v136, 1.0, v136
	v_add_f32_e32 v151, 1.0, v153
	v_rcp_f32_e32 v153, v151
	v_rcp_f32_e32 v151, v136
	v_pk_mul_f32 v[148:149], v[126:127], v[148:149]
	v_pk_mul_f32 v[146:147], v[124:125], v[146:147]
	v_pk_mul_f32 v[152:153], v[122:123], v[152:153]
	v_pk_mul_f32 v[150:151], v[120:121], v[150:151]
	s_mov_b64 s[8:9], 0

; __device__ __forceinline__ u32x4 pack8(const float (&f)[8]) { u32x4 w; w.x = cvt_pk_bf16(f[0], f[1]); w.y = cvt_pk_bf16(f[2], f[3]); w.z = cvt_pk_bf16(f[4], f[5]); w.w = cvt_pk_bf16(f[6], f[7]); return w; }
; __device__ __forceinline__ float sigm(float x) { return __builtin_amdgcn_rcpf(1.f + __builtin_amdgcn_exp2f(-1.4426950408889634f * x)); }
;     __device__ __forceinline__ void operator()(const f32x4 (&acc)[2][2][4][2], const Unit& u, int wr, int wc, int fr, int fq) const {
;         const int pn = u.pn; const int row0 = u.pm * BM + wr * 64 + fr;
;         size_t off; int ldc = 1024, colt, act = 0;
;         if (pn < 16) { off = WS_QK + (size_t)(pn >> 2) * (64 * MiB); colt = (pn & 3) * 256; if ((pn >> 2) == 2) act = 2; }
;         else if (pn < 18) { off = WS_SKV; ldc = 512; colt = (pn - 16) * 256; }
;         else if (pn < 22) { off = WS_GA; colt = (pn - 18) * 256; act = 1; }
;         else { off = WS_GB; colt = (pn - 22) * 256; act = 1; }
;         bf16_t* base = (bf16_t*)(ws + off);
;         const int col0 = colt + wc * 32 + 8 * fq;
; #pragma unroll
;         for (int ai = 0; ai < 2; ++ai)
; #pragma unroll
;             for (int m = 0; m < 4; ++m) { bf16_t* rowp = base + (size_t)(row0 + ai * HALF + m * 16) * ldc + col0;
; #pragma unroll
;                 for (int bj = 0; bj < 2; ++bj) { const f32x4 v0 = acc[ai][bj][m][0], v1 = acc[ai][bj][m][1];
;                     float f[8] = {v0[0], v0[1], v0[2], v0[3], v1[0], v1[1], v1[2], v1[3]};
;                     if (act == 1) {
; #pragma unroll
;                         for (int e = 0; e < 8; ++e) f[e] = sigm(f[e]);
;                     } else if (act == 2) {
; #pragma unroll
;                         for (int e = 0; e < 8; ++e) f[e] = f[e] * sigm(f[e]);
;                     }
;                     __builtin_nontemporal_store(pack8(f), (u32x4*)(rowp + bj * HALF)); } }
.Lp1_plain:
	v_lshl_add_u32 v160, s6, 8, v154
	v_add_u32_e32 v136, s3, v156
	s_add_u32 s98, s68, s80
	s_addc_u32 s99, s69, s81
	s_lshl_b32 s100, s78, 1
	v_mul_lo_u32 v160, v160, s100
	s_lshl_b32 s100, s78, 5
	v_lshl_add_u32 v160, v136, 1, v160
	v_cvt_pk_bf16_f32 v124, v124, v125
	v_cvt_pk_bf16_f32 v125, v126, v127
	v_cvt_pk_bf16_f32 v126, v120, v121
	v_cvt_pk_bf16_f32 v127, v122, v123
	ds_write_b128 v228, v[124:127]
	ds_read_b128 v[120:123], v229
	v_cvt_pk_bf16_f32 v116, v116, v117
	v_cvt_pk_bf16_f32 v117, v118, v119
	v_cvt_pk_bf16_f32 v118, v112, v113
	v_cvt_pk_bf16_f32 v119, v114, v115
	ds_write_b128 v228, v[116:119]
	ds_read_b128 v[112:115], v229
	v_cvt_pk_bf16_f32 v108, v108, v109
	v_cvt_pk_bf16_f32 v109, v110, v111
	v_cvt_pk_bf16_f32 v110, v104, v105
	v_cvt_pk_bf16_f32 v111, v106, v107
	ds_write_b128 v228, v[108:111]
	ds_read_b128 v[104:107], v229
	v_cvt_pk_bf16_f32 v100, v100, v101
	v_cvt_pk_bf16_f32 v101, v102, v103
	v_cvt_pk_bf16_f32 v102, v96, v97
	v_cvt_pk_bf16_f32 v103, v98, v99
	ds_write_b128 v228, v[100:103]
	ds_read_b128 v[96:99], v229
	s_waitcnt lgkmcnt(6)
	global_store_dwordx4 v160, v[120:123], s[98:99] nt
	s_waitcnt lgkmcnt(4)
	global_store_dwordx4 v160, v[112:115], s[98:99] offset:256 nt
	v_add_u32_e32 v160, s100, v160
	s_waitcnt lgkmcnt(2)
	global_store_dwordx4 v160, v[104:107], s[98:99] nt
	s_waitcnt lgkmcnt(0)
	global_store_dwordx4 v160, v[96:99], s[98:99] offset:256 nt
	v_cvt_pk_bf16_f32 v92, v92, v93
	v_cvt_pk_bf16_f32 v93, v94, v95
	v_cvt_pk_bf16_f32 v94, v88, v89
	v_cvt_pk_bf16_f32 v95, v90, v91
	ds_write_b128 v228, v[92:95]
	ds_read_b128 v[88:91], v229
	v_cvt_pk_bf16_f32 v84, v84, v85
	v_cvt_pk_bf16_f32 v85, v86, v87
	v_cvt_pk_bf16_f32 v86, v80, v81
	v_cvt_pk_bf16_f32 v87, v82, v83
	ds_write_b128 v228, v[84:87]
	ds_read_b128 v[80:83], v229
	v_cvt_pk_bf16_f32 v76, v76, v77
	v_cvt_pk_bf16_f32 v77, v78, v79
	v_cvt_pk_bf16_f32 v78, v72, v73
	v_cvt_pk_bf16_f32 v79, v74, v75
	ds_write_b128 v228, v[76:79]
	ds_read_b128 v[72:75], v229
	v_cvt_pk_bf16_f32 v68, v68, v69
	v_cvt_pk_bf16_f32 v69, v70, v71
	v_cvt_pk_bf16_f32 v70, v64, v65
	v_cvt_pk_bf16_f32 v71, v66, v67
	ds_write_b128 v228, v[68:71]
	ds_read_b128 v[64:67], v229
	v_add_u32_e32 v160, s100, v160
	s_waitcnt lgkmcnt(6)
	global_store_dwordx4 v160, v[88:91], s[98:99] nt
	s_waitcnt lgkmcnt(4)
	global_store_dwordx4 v160, v[80:83], s[98:99] offset:256 nt
	v_add_u32_e32 v160, s100, v160
	s_waitcnt lgkmcnt(2)
	global_store_dwordx4 v160, v[72:75], s[98:99] nt
	s_waitcnt lgkmcnt(0)
	global_store_dwordx4 v160, v[64:67], s[98:99] offset:256 nt
	v_cvt_pk_bf16_f32 v60, v60, v61
	v_cvt_pk_bf16_f32 v61, v62, v63
	v_cvt_pk_bf16_f32 v62, v56, v57
	v_cvt_pk_bf16_f32 v63, v58, v59
	ds_write_b128 v228, v[60:63]
	ds_read_b128 v[56:59], v229
	v_cvt_pk_bf16_f32 v52, v52, v53
	v_cvt_pk_bf16_f32 v53, v54, v55
	v_cvt_pk_bf16_f32 v54, v48, v49
	v_cvt_pk_bf16_f32 v55, v50, v51
	ds_write_b128 v228, v[52:55]
	ds_read_b128 v[48:51], v229
	v_cvt_pk_bf16_f32 v44, v44, v45
	v_cvt_pk_bf16_f32 v45, v46, v47
	v_cvt_pk_bf16_f32 v46, v40, v41
	v_cvt_pk_bf16_f32 v47, v42, v43
	ds_write_b128 v228, v[44:47]
	ds_read_b128 v[40:43], v229
	v_cvt_pk_bf16_f32 v36, v36, v37
	v_cvt_pk_bf16_f32 v37, v38, v39
	v_cvt_pk_bf16_f32 v38, v32, v33
	v_cvt_pk_bf16_f32 v39, v34, v35
	ds_write_b128 v228, v[36:39]
	ds_read_b128 v[32:35], v229
	v_mad_u32_u24 v160, s100, 5, v160
	s_waitcnt lgkmcnt(6)
	global_store_dwordx4 v160, v[56:59], s[98:99] nt
	s_waitcnt lgkmcnt(4)
	global_store_dwordx4 v160, v[48:51], s[98:99] offset:256 nt
	v_add_u32_e32 v160, s100, v160
	s_waitcnt lgkmcnt(2)
	global_store_dwordx4 v160, v[40:43], s[98:99] nt
	s_waitcnt lgkmcnt(0)
	global_store_dwordx4 v160, v[32:35], s[98:99] offset:256 nt
	v_cvt_pk_bf16_f32 v28, v28, v29
	v_cvt_pk_bf16_f32 v29, v30, v31
	v_cvt_pk_bf16_f32 v30, v24, v25
	v_cvt_pk_bf16_f32 v31, v26, v27
	ds_write_b128 v228, v[28:31]
	ds_read_b128 v[24:27], v229
	v_cvt_pk_bf16_f32 v20, v20, v21
	v_cvt_pk_bf16_f32 v21, v22, v23
	v_cvt_pk_bf16_f32 v22, v16, v17
	v_cvt_pk_bf16_f32 v23, v18, v19
	ds_write_b128 v228, v[20:23]
	ds_read_b128 v[16:19], v229
	v_cvt_pk_bf16_f32 v12, v12, v13
	v_cvt_pk_bf16_f32 v13, v14, v15
	v_cvt_pk_bf16_f32 v14, v8, v9
	v_cvt_pk_bf16_f32 v15, v10, v11
	ds_write_b128 v228, v[12:15]
	ds_read_b128 v[8:11], v229
	v_cvt_pk_bf16_f32 v4, v4, v5
	v_cvt_pk_bf16_f32 v5, v6, v7
	v_cvt_pk_bf16_f32 v6, v0, v1
	v_cvt_pk_bf16_f32 v7, v2, v3
	ds_write_b128 v228, v[4:7]
	ds_read_b128 v[0:3], v229
	v_add_u32_e32 v160, s100, v160
	s_waitcnt lgkmcnt(6)
	global_store_dwordx4 v160, v[24:27], s[98:99] nt
	s_waitcnt lgkmcnt(4)
	global_store_dwordx4 v160, v[16:19], s[98:99] offset:256 nt
	v_add_u32_e32 v160, s100, v160
	s_waitcnt lgkmcnt(2)
	global_store_dwordx4 v160, v[8:11], s[98:99] nt
	s_waitcnt lgkmcnt(0)
	global_store_dwordx4 v160, v[0:3], s[98:99] offset:256 nt
	s_andn2_b64 vcc, exec, s[0:1]
	s_mov_b64 s[0:1], -1
	s_branch .Lp1_tail
; __device__ __forceinline__ u32x4 pack8(const float (&f)[8]) { u32x4 w; w.x = cvt_pk_bf16(f[0], f[1]); w.y = cvt_pk_bf16(f[2], f[3]); w.z = cvt_pk_bf16(f[4], f[5]); w.w = cvt_pk_bf16(f[6], f[7]); return w; }
; __device__ __forceinline__ float sigm(float x) { return __builtin_amdgcn_rcpf(1.f + __builtin_amdgcn_exp2f(-1.4426950408889634f * x)); }
;     __device__ __forceinline__ void operator()(const f32x4 (&acc)[2][2][4][2], const Unit& u, int wr, int wc, int fr, int fq) const {
;     ...
;                     } else if (act == 2) {
; #pragma unroll
;                         for (int e = 0; e < 8; ++e) f[e] = f[e] * sigm(f[e]);
;                     }
;                     __builtin_nontemporal_store(pack8(f), (u32x4*)(rowp + bj * HALF)); } }
.Lp1_silu:
	v_lshl_add_u32 v160, s6, 8, v154
	v_add_u32_e32 v136, s3, v156
	s_add_u32 s98, s68, s80
	s_addc_u32 s99, s69, s81
	s_lshl_b32 s100, s78, 1
	v_mul_lo_u32 v160, v160, s100
	s_lshl_b32 s100, s78, 5
	v_lshl_add_u32 v160, v136, 1, v160
	v_mov_b32_e32 v230, 0xbfb8aa3b
	v_mov_b32_e32 v231, 0xbfb8aa3b
	v_mov_b32_e32 v232, 1.0
	v_mov_b32_e32 v233, 1.0
	v_pk_mul_f32 v[234:235], v[124:125], v[230:231]
	v_pk_mul_f32 v[236:237], v[126:127], v[230:231]
	v_pk_mul_f32 v[238:239], v[120:121], v[230:231]
	v_pk_mul_f32 v[240:241], v[122:123], v[230:231]
	v_exp_f32_e32 v234, v234
	v_exp_f32_e32 v235, v235
	v_exp_f32_e32 v236, v236
	v_exp_f32_e32 v237, v237
	v_exp_f32_e32 v238, v238
	v_exp_f32_e32 v239, v239
	v_exp_f32_e32 v240, v240
	v_exp_f32_e32 v241, v241
	v_pk_add_f32 v[234:235], v[234:235], v[232:233]
	v_pk_add_f32 v[236:237], v[236:237], v[232:233]
	v_pk_add_f32 v[238:239], v[238:239], v[232:233]
	v_pk_add_f32 v[240:241], v[240:241], v[232:233]
	v_rcp_f32_e32 v234, v234
	v_rcp_f32_e32 v235, v235
	v_rcp_f32_e32 v236, v236
	v_rcp_f32_e32 v237, v237
	v_rcp_f32_e32 v238, v238
	v_rcp_f32_e32 v239, v239
	v_rcp_f32_e32 v240, v240
	v_rcp_f32_e32 v241, v241
	v_pk_mul_f32 v[234:235], v[124:125], v[234:235]
	v_pk_mul_f32 v[236:237], v[126:127], v[236:237]
	v_pk_mul_f32 v[238:239], v[120:121], v[238:239]
	v_pk_mul_f32 v[240:241], v[122:123], v[240:241]
	v_cvt_pk_bf16_f32 v124, v234, v235
	v_cvt_pk_bf16_f32 v125, v236, v237
	v_cvt_pk_bf16_f32 v126, v238, v239
	v_cvt_pk_bf16_f32 v127, v240, v241
	ds_write_b128 v228, v[124:127]
	ds_read_b128 v[120:123], v229
	v_pk_mul_f32 v[234:235], v[116:117], v[230:231]
	v_pk_mul_f32 v[236:237], v[118:119], v[230:231]
	v_pk_mul_f32 v[238:239], v[112:113], v[230:231]
	v_pk_mul_f32 v[240:241], v[114:115], v[230:231]
	v_exp_f32_e32 v234, v234
	v_exp_f32_e32 v235, v235
	v_exp_f32_e32 v236, v236
	v_exp_f32_e32 v237, v237
	v_exp_f32_e32 v238, v238
	v_exp_f32_e32 v239, v239
	v_exp_f32_e32 v240, v240
	v_exp_f32_e32 v241, v241
	v_pk_add_f32 v[234:235], v[234:235], v[232:233]
	v_pk_add_f32 v[236:237], v[236:237], v[232:233]
	v_pk_add_f32 v[238:239], v[238:239], v[232:233]
	v_pk_add_f32 v[240:241], v[240:241], v[232:233]
	v_rcp_f32_e32 v234, v234
	v_rcp_f32_e32 v235, v235
	v_rcp_f32_e32 v236, v236
	v_rcp_f32_e32 v237, v237
	v_rcp_f32_e32 v238, v238
	v_rcp_f32_e32 v239, v239
	v_rcp_f32_e32 v240, v240
	v_rcp_f32_e32 v241, v241
	v_pk_mul_f32 v[234:235], v[116:117], v[234:235]
	v_pk_mul_f32 v[236:237], v[118:119], v[236:237]
	v_pk_mul_f32 v[238:239], v[112:113], v[238:239]
	v_pk_mul_f32 v[240:241], v[114:115], v[240:241]
	v_cvt_pk_bf16_f32 v116, v234, v235
	v_cvt_pk_bf16_f32 v117, v236, v237
	v_cvt_pk_bf16_f32 v118, v238, v239
	v_cvt_pk_bf16_f32 v119, v240, v241
	ds_write_b128 v228, v[116:119]
	ds_read_b128 v[112:115], v229
	v_pk_mul_f32 v[234:235], v[108:109], v[230:231]
	v_pk_mul_f32 v[236:237], v[110:111], v[230:231]
	v_pk_mul_f32 v[238:239], v[104:105], v[230:231]
	v_pk_mul_f32 v[240:241], v[106:107], v[230:231]
	v_exp_f32_e32 v234, v234
	v_exp_f32_e32 v235, v235
	v_exp_f32_e32 v236, v236
	v_exp_f32_e32 v237, v237
	v_exp_f32_e32 v238, v238
	v_exp_f32_e32 v239, v239
	v_exp_f32_e32 v240, v240
	v_exp_f32_e32 v241, v241
	v_pk_add_f32 v[234:235], v[234:235], v[232:233]
	v_pk_add_f32 v[236:237], v[236:237], v[232:233]
	v_pk_add_f32 v[238:239], v[238:239], v[232:233]
	v_pk_add_f32 v[240:241], v[240:241], v[232:233]
	v_rcp_f32_e32 v234, v234
	v_rcp_f32_e32 v235, v235
	v_rcp_f32_e32 v236, v236
	v_rcp_f32_e32 v237, v237
	v_rcp_f32_e32 v238, v238
	v_rcp_f32_e32 v239, v239
	v_rcp_f32_e32 v240, v240
	v_rcp_f32_e32 v241, v241
	v_pk_mul_f32 v[234:235], v[108:109], v[234:235]
	v_pk_mul_f32 v[236:237], v[110:111], v[236:237]
	v_pk_mul_f32 v[238:239], v[104:105], v[238:239]
	v_pk_mul_f32 v[240:241], v[106:107], v[240:241]
	v_cvt_pk_bf16_f32 v108, v234, v235
	v_cvt_pk_bf16_f32 v109, v236, v237
	v_cvt_pk_bf16_f32 v110, v238, v239
	v_cvt_pk_bf16_f32 v111, v240, v241
	ds_write_b128 v228, v[108:111]
	ds_read_b128 v[104:107], v229
	v_pk_mul_f32 v[234:235], v[100:101], v[230:231]
	v_pk_mul_f32 v[236:237], v[102:103], v[230:231]
	v_pk_mul_f32 v[238:239], v[96:97], v[230:231]
	v_pk_mul_f32 v[240:241], v[98:99], v[230:231]
	v_exp_f32_e32 v234, v234
	v_exp_f32_e32 v235, v235
	v_exp_f32_e32 v236, v236
	v_exp_f32_e32 v237, v237
	v_exp_f32_e32 v238, v238
	v_exp_f32_e32 v239, v239
	v_exp_f32_e32 v240, v240
	v_exp_f32_e32 v241, v241
	v_pk_add_f32 v[234:235], v[234:235], v[232:233]
	v_pk_add_f32 v[236:237], v[236:237], v[232:233]
	v_pk_add_f32 v[238:239], v[238:239], v[232:233]
	v_pk_add_f32 v[240:241], v[240:241], v[232:233]
	v_rcp_f32_e32 v234, v234
	v_rcp_f32_e32 v235, v235
	v_rcp_f32_e32 v236, v236
	v_rcp_f32_e32 v237, v237
	v_rcp_f32_e32 v238, v238
	v_rcp_f32_e32 v239, v239
	v_rcp_f32_e32 v240, v240
	v_rcp_f32_e32 v241, v241
	v_pk_mul_f32 v[234:235], v[100:101], v[234:235]
	v_pk_mul_f32 v[236:237], v[102:103], v[236:237]
	v_pk_mul_f32 v[238:239], v[96:97], v[238:239]
	v_pk_mul_f32 v[240:241], v[98:99], v[240:241]
	v_cvt_pk_bf16_f32 v100, v234, v235
	v_cvt_pk_bf16_f32 v101, v236, v237
	v_cvt_pk_bf16_f32 v102, v238, v239
	v_cvt_pk_bf16_f32 v103, v240, v241
	ds_write_b128 v228, v[100:103]
	ds_read_b128 v[96:99], v229
	s_waitcnt lgkmcnt(6)
	global_store_dwordx4 v160, v[120:123], s[98:99] nt
	s_waitcnt lgkmcnt(4)
	global_store_dwordx4 v160, v[112:115], s[98:99] offset:256 nt
	v_add_u32_e32 v160, s100, v160
	s_waitcnt lgkmcnt(2)
	global_store_dwordx4 v160, v[104:107], s[98:99] nt
	s_waitcnt lgkmcnt(0)
; __device__ __forceinline__ u32x4 pack8(const float (&f)[8]) { u32x4 w; w.x = cvt_pk_bf16(f[0], f[1]); w.y = cvt_pk_bf16(f[2], f[3]); w.z = cvt_pk_bf16(f[4], f[5]); w.w = cvt_pk_bf16(f[6], f[7]); return w; }
; __device__ __forceinline__ float sigm(float x) { return __builtin_amdgcn_rcpf(1.f + __builtin_amdgcn_exp2f(-1.4426950408889634f * x)); }
;     __device__ __forceinline__ void operator()(const f32x4 (&acc)[2][2][4][2], const Unit& u, int wr, int wc, int fr, int fq) const {
;     ...
;                     } else if (act == 2) {
; #pragma unroll
;                         for (int e = 0; e < 8; ++e) f[e] = f[e] * sigm(f[e]);
;                     }
;                     __builtin_nontemporal_store(pack8(f), (u32x4*)(rowp + bj * HALF)); } }
	global_store_dwordx4 v160, v[96:99], s[98:99] offset:256 nt
	v_pk_mul_f32 v[234:235], v[92:93], v[230:231]
	v_pk_mul_f32 v[236:237], v[94:95], v[230:231]
	v_pk_mul_f32 v[238:239], v[88:89], v[230:231]
	v_pk_mul_f32 v[240:241], v[90:91], v[230:231]
	v_exp_f32_e32 v234, v234
	v_exp_f32_e32 v235, v235
	v_exp_f32_e32 v236, v236
	v_exp_f32_e32 v237, v237
	v_exp_f32_e32 v238, v238
	v_exp_f32_e32 v239, v239
	v_exp_f32_e32 v240, v240
	v_exp_f32_e32 v241, v241
	v_pk_add_f32 v[234:235], v[234:235], v[232:233]
	v_pk_add_f32 v[236:237], v[236:237], v[232:233]
	v_pk_add_f32 v[238:239], v[238:239], v[232:233]
	v_pk_add_f32 v[240:241], v[240:241], v[232:233]
	v_rcp_f32_e32 v234, v234
	v_rcp_f32_e32 v235, v235
	v_rcp_f32_e32 v236, v236
	v_rcp_f32_e32 v237, v237
	v_rcp_f32_e32 v238, v238
	v_rcp_f32_e32 v239, v239
	v_rcp_f32_e32 v240, v240
	v_rcp_f32_e32 v241, v241
	v_pk_mul_f32 v[234:235], v[92:93], v[234:235]
	v_pk_mul_f32 v[236:237], v[94:95], v[236:237]
	v_pk_mul_f32 v[238:239], v[88:89], v[238:239]
	v_pk_mul_f32 v[240:241], v[90:91], v[240:241]
	v_cvt_pk_bf16_f32 v92, v234, v235
	v_cvt_pk_bf16_f32 v93, v236, v237
	v_cvt_pk_bf16_f32 v94, v238, v239
	v_cvt_pk_bf16_f32 v95, v240, v241
	ds_write_b128 v228, v[92:95]
	ds_read_b128 v[88:91], v229
	v_pk_mul_f32 v[234:235], v[84:85], v[230:231]
	v_pk_mul_f32 v[236:237], v[86:87], v[230:231]
	v_pk_mul_f32 v[238:239], v[80:81], v[230:231]
	v_pk_mul_f32 v[240:241], v[82:83], v[230:231]
	v_exp_f32_e32 v234, v234
	v_exp_f32_e32 v235, v235
	v_exp_f32_e32 v236, v236
	v_exp_f32_e32 v237, v237
	v_exp_f32_e32 v238, v238
	v_exp_f32_e32 v239, v239
	v_exp_f32_e32 v240, v240
	v_exp_f32_e32 v241, v241
	v_pk_add_f32 v[234:235], v[234:235], v[232:233]
	v_pk_add_f32 v[236:237], v[236:237], v[232:233]
	v_pk_add_f32 v[238:239], v[238:239], v[232:233]
	v_pk_add_f32 v[240:241], v[240:241], v[232:233]
	v_rcp_f32_e32 v234, v234
	v_rcp_f32_e32 v235, v235
	v_rcp_f32_e32 v236, v236
	v_rcp_f32_e32 v237, v237
	v_rcp_f32_e32 v238, v238
	v_rcp_f32_e32 v239, v239
	v_rcp_f32_e32 v240, v240
	v_rcp_f32_e32 v241, v241
	v_pk_mul_f32 v[234:235], v[84:85], v[234:235]
	v_pk_mul_f32 v[236:237], v[86:87], v[236:237]
	v_pk_mul_f32 v[238:239], v[80:81], v[238:239]
	v_pk_mul_f32 v[240:241], v[82:83], v[240:241]
	v_cvt_pk_bf16_f32 v84, v234, v235
	v_cvt_pk_bf16_f32 v85, v236, v237
	v_cvt_pk_bf16_f32 v86, v238, v239
	v_cvt_pk_bf16_f32 v87, v240, v241
	ds_write_b128 v228, v[84:87]
	ds_read_b128 v[80:83], v229
	v_pk_mul_f32 v[234:235], v[76:77], v[230:231]
	v_pk_mul_f32 v[236:237], v[78:79], v[230:231]
	v_pk_mul_f32 v[238:239], v[72:73], v[230:231]
	v_pk_mul_f32 v[240:241], v[74:75], v[230:231]
	v_exp_f32_e32 v234, v234
	v_exp_f32_e32 v235, v235
	v_exp_f32_e32 v236, v236
	v_exp_f32_e32 v237, v237
	v_exp_f32_e32 v238, v238
	v_exp_f32_e32 v239, v239
	v_exp_f32_e32 v240, v240
	v_exp_f32_e32 v241, v241
	v_pk_add_f32 v[234:235], v[234:235], v[232:233]
	v_pk_add_f32 v[236:237], v[236:237], v[232:233]
	v_pk_add_f32 v[238:239], v[238:239], v[232:233]
	v_pk_add_f32 v[240:241], v[240:241], v[232:233]
	v_rcp_f32_e32 v234, v234
	v_rcp_f32_e32 v235, v235
	v_rcp_f32_e32 v236, v236
	v_rcp_f32_e32 v237, v237
	v_rcp_f32_e32 v238, v238
	v_rcp_f32_e32 v239, v239
	v_rcp_f32_e32 v240, v240
	v_rcp_f32_e32 v241, v241
	v_pk_mul_f32 v[234:235], v[76:77], v[234:235]
	v_pk_mul_f32 v[236:237], v[78:79], v[236:237]
	v_pk_mul_f32 v[238:239], v[72:73], v[238:239]
	v_pk_mul_f32 v[240:241], v[74:75], v[240:241]
	v_cvt_pk_bf16_f32 v76, v234, v235
	v_cvt_pk_bf16_f32 v77, v236, v237
	v_cvt_pk_bf16_f32 v78, v238, v239
	v_cvt_pk_bf16_f32 v79, v240, v241
	ds_write_b128 v228, v[76:79]
	ds_read_b128 v[72:75], v229
	v_pk_mul_f32 v[234:235], v[68:69], v[230:231]
	v_pk_mul_f32 v[236:237], v[70:71], v[230:231]
	v_pk_mul_f32 v[238:239], v[64:65], v[230:231]
	v_pk_mul_f32 v[240:241], v[66:67], v[230:231]
	v_exp_f32_e32 v234, v234
	v_exp_f32_e32 v235, v235
	v_exp_f32_e32 v236, v236
	v_exp_f32_e32 v237, v237
	v_exp_f32_e32 v238, v238
	v_exp_f32_e32 v239, v239
	v_exp_f32_e32 v240, v240
	v_exp_f32_e32 v241, v241
	v_pk_add_f32 v[234:235], v[234:235], v[232:233]
	v_pk_add_f32 v[236:237], v[236:237], v[232:233]
	v_pk_add_f32 v[238:239], v[238:239], v[232:233]
	v_pk_add_f32 v[240:241], v[240:241], v[232:233]
	v_rcp_f32_e32 v234, v234
	v_rcp_f32_e32 v235, v235
	v_rcp_f32_e32 v236, v236
	v_rcp_f32_e32 v237, v237
	v_rcp_f32_e32 v238, v238
	v_rcp_f32_e32 v239, v239
	v_rcp_f32_e32 v240, v240
	v_rcp_f32_e32 v241, v241
	v_pk_mul_f32 v[234:235], v[68:69], v[234:235]
	v_pk_mul_f32 v[236:237], v[70:71], v[236:237]
	v_pk_mul_f32 v[238:239], v[64:65], v[238:239]
	v_pk_mul_f32 v[240:241], v[66:67], v[240:241]
	v_cvt_pk_bf16_f32 v68, v234, v235
	v_cvt_pk_bf16_f32 v69, v236, v237
	v_cvt_pk_bf16_f32 v70, v238, v239
	v_cvt_pk_bf16_f32 v71, v240, v241
	ds_write_b128 v228, v[68:71]
	ds_read_b128 v[64:67], v229
	v_add_u32_e32 v160, s100, v160
	s_waitcnt lgkmcnt(6)
	global_store_dwordx4 v160, v[88:91], s[98:99] nt
	s_waitcnt lgkmcnt(4)
	global_store_dwordx4 v160, v[80:83], s[98:99] offset:256 nt
	v_add_u32_e32 v160, s100, v160
	s_waitcnt lgkmcnt(2)
	global_store_dwordx4 v160, v[72:75], s[98:99] nt
	s_waitcnt lgkmcnt(0)
; __device__ __forceinline__ u32x4 pack8(const float (&f)[8]) { u32x4 w; w.x = cvt_pk_bf16(f[0], f[1]); w.y = cvt_pk_bf16(f[2], f[3]); w.z = cvt_pk_bf16(f[4], f[5]); w.w = cvt_pk_bf16(f[6], f[7]); return w; }
; __device__ __forceinline__ float sigm(float x) { return __builtin_amdgcn_rcpf(1.f + __builtin_amdgcn_exp2f(-1.4426950408889634f * x)); }
;     __device__ __forceinline__ void operator()(const f32x4 (&acc)[2][2][4][2], const Unit& u, int wr, int wc, int fr, int fq) const {
;     ...
;                     } else if (act == 2) {
; #pragma unroll
;                         for (int e = 0; e < 8; ++e) f[e] = f[e] * sigm(f[e]);
;                     }
;                     __builtin_nontemporal_store(pack8(f), (u32x4*)(rowp + bj * HALF)); } }
	global_store_dwordx4 v160, v[64:67], s[98:99] offset:256 nt
	v_pk_mul_f32 v[234:235], v[60:61], v[230:231]
	v_pk_mul_f32 v[236:237], v[62:63], v[230:231]
	v_pk_mul_f32 v[238:239], v[56:57], v[230:231]
	v_pk_mul_f32 v[240:241], v[58:59], v[230:231]
	v_exp_f32_e32 v234, v234
	v_exp_f32_e32 v235, v235
	v_exp_f32_e32 v236, v236
	v_exp_f32_e32 v237, v237
	v_exp_f32_e32 v238, v238
	v_exp_f32_e32 v239, v239
	v_exp_f32_e32 v240, v240
	v_exp_f32_e32 v241, v241
	v_pk_add_f32 v[234:235], v[234:235], v[232:233]
	v_pk_add_f32 v[236:237], v[236:237], v[232:233]
	v_pk_add_f32 v[238:239], v[238:239], v[232:233]
	v_pk_add_f32 v[240:241], v[240:241], v[232:233]
	v_rcp_f32_e32 v234, v234
	v_rcp_f32_e32 v235, v235
	v_rcp_f32_e32 v236, v236
	v_rcp_f32_e32 v237, v237
	v_rcp_f32_e32 v238, v238
	v_rcp_f32_e32 v239, v239
	v_rcp_f32_e32 v240, v240
	v_rcp_f32_e32 v241, v241
	v_pk_mul_f32 v[234:235], v[60:61], v[234:235]
	v_pk_mul_f32 v[236:237], v[62:63], v[236:237]
	v_pk_mul_f32 v[238:239], v[56:57], v[238:239]
	v_pk_mul_f32 v[240:241], v[58:59], v[240:241]
	v_cvt_pk_bf16_f32 v60, v234, v235
	v_cvt_pk_bf16_f32 v61, v236, v237
	v_cvt_pk_bf16_f32 v62, v238, v239
	v_cvt_pk_bf16_f32 v63, v240, v241
	ds_write_b128 v228, v[60:63]
	ds_read_b128 v[56:59], v229
	v_pk_mul_f32 v[234:235], v[52:53], v[230:231]
	v_pk_mul_f32 v[236:237], v[54:55], v[230:231]
	v_pk_mul_f32 v[238:239], v[48:49], v[230:231]
	v_pk_mul_f32 v[240:241], v[50:51], v[230:231]
	v_exp_f32_e32 v234, v234
	v_exp_f32_e32 v235, v235
	v_exp_f32_e32 v236, v236
	v_exp_f32_e32 v237, v237
	v_exp_f32_e32 v238, v238
	v_exp_f32_e32 v239, v239
	v_exp_f32_e32 v240, v240
	v_exp_f32_e32 v241, v241
	v_pk_add_f32 v[234:235], v[234:235], v[232:233]
	v_pk_add_f32 v[236:237], v[236:237], v[232:233]
	v_pk_add_f32 v[238:239], v[238:239], v[232:233]
	v_pk_add_f32 v[240:241], v[240:241], v[232:233]
	v_rcp_f32_e32 v234, v234
	v_rcp_f32_e32 v235, v235
	v_rcp_f32_e32 v236, v236
	v_rcp_f32_e32 v237, v237
	v_rcp_f32_e32 v238, v238
	v_rcp_f32_e32 v239, v239
	v_rcp_f32_e32 v240, v240
	v_rcp_f32_e32 v241, v241
	v_pk_mul_f32 v[234:235], v[52:53], v[234:235]
	v_pk_mul_f32 v[236:237], v[54:55], v[236:237]
	v_pk_mul_f32 v[238:239], v[48:49], v[238:239]
	v_pk_mul_f32 v[240:241], v[50:51], v[240:241]
	v_cvt_pk_bf16_f32 v52, v234, v235
	v_cvt_pk_bf16_f32 v53, v236, v237
	v_cvt_pk_bf16_f32 v54, v238, v239
	v_cvt_pk_bf16_f32 v55, v240, v241
	ds_write_b128 v228, v[52:55]
	ds_read_b128 v[48:51], v229
	v_pk_mul_f32 v[234:235], v[44:45], v[230:231]
	v_pk_mul_f32 v[236:237], v[46:47], v[230:231]
	v_pk_mul_f32 v[238:239], v[40:41], v[230:231]
	v_pk_mul_f32 v[240:241], v[42:43], v[230:231]
	v_exp_f32_e32 v234, v234
	v_exp_f32_e32 v235, v235
	v_exp_f32_e32 v236, v236
	v_exp_f32_e32 v237, v237
	v_exp_f32_e32 v238, v238
	v_exp_f32_e32 v239, v239
	v_exp_f32_e32 v240, v240
	v_exp_f32_e32 v241, v241
	v_pk_add_f32 v[234:235], v[234:235], v[232:233]
	v_pk_add_f32 v[236:237], v[236:237], v[232:233]
	v_pk_add_f32 v[238:239], v[238:239], v[232:233]
	v_pk_add_f32 v[240:241], v[240:241], v[232:233]
	v_rcp_f32_e32 v234, v234
	v_rcp_f32_e32 v235, v235
	v_rcp_f32_e32 v236, v236
	v_rcp_f32_e32 v237, v237
	v_rcp_f32_e32 v238, v238
	v_rcp_f32_e32 v239, v239
	v_rcp_f32_e32 v240, v240
	v_rcp_f32_e32 v241, v241
	v_pk_mul_f32 v[234:235], v[44:45], v[234:235]
	v_pk_mul_f32 v[236:237], v[46:47], v[236:237]
	v_pk_mul_f32 v[238:239], v[40:41], v[238:239]
	v_pk_mul_f32 v[240:241], v[42:43], v[240:241]
	v_cvt_pk_bf16_f32 v44, v234, v235
	v_cvt_pk_bf16_f32 v45, v236, v237
	v_cvt_pk_bf16_f32 v46, v238, v239
	v_cvt_pk_bf16_f32 v47, v240, v241
	ds_write_b128 v228, v[44:47]
	ds_read_b128 v[40:43], v229
	v_pk_mul_f32 v[234:235], v[36:37], v[230:231]
	v_pk_mul_f32 v[236:237], v[38:39], v[230:231]
	v_pk_mul_f32 v[238:239], v[32:33], v[230:231]
	v_pk_mul_f32 v[240:241], v[34:35], v[230:231]
	v_exp_f32_e32 v234, v234
	v_exp_f32_e32 v235, v235
	v_exp_f32_e32 v236, v236
	v_exp_f32_e32 v237, v237
	v_exp_f32_e32 v238, v238
	v_exp_f32_e32 v239, v239
	v_exp_f32_e32 v240, v240
	v_exp_f32_e32 v241, v241
	v_pk_add_f32 v[234:235], v[234:235], v[232:233]
	v_pk_add_f32 v[236:237], v[236:237], v[232:233]
	v_pk_add_f32 v[238:239], v[238:239], v[232:233]
	v_pk_add_f32 v[240:241], v[240:241], v[232:233]
	v_rcp_f32_e32 v234, v234
	v_rcp_f32_e32 v235, v235
	v_rcp_f32_e32 v236, v236
	v_rcp_f32_e32 v237, v237
	v_rcp_f32_e32 v238, v238
	v_rcp_f32_e32 v239, v239
	v_rcp_f32_e32 v240, v240
	v_rcp_f32_e32 v241, v241
	v_pk_mul_f32 v[234:235], v[36:37], v[234:235]
	v_pk_mul_f32 v[236:237], v[38:39], v[236:237]
	v_pk_mul_f32 v[238:239], v[32:33], v[238:239]
	v_pk_mul_f32 v[240:241], v[34:35], v[240:241]
	v_cvt_pk_bf16_f32 v36, v234, v235
	v_cvt_pk_bf16_f32 v37, v236, v237
	v_cvt_pk_bf16_f32 v38, v238, v239
	v_cvt_pk_bf16_f32 v39, v240, v241
	ds_write_b128 v228, v[36:39]
	ds_read_b128 v[32:35], v229
	v_mad_u32_u24 v160, s100, 5, v160
	s_waitcnt lgkmcnt(6)
	global_store_dwordx4 v160, v[56:59], s[98:99] nt
	s_waitcnt lgkmcnt(4)
	global_store_dwordx4 v160, v[48:51], s[98:99] offset:256 nt
	v_add_u32_e32 v160, s100, v160
	s_waitcnt lgkmcnt(2)
	global_store_dwordx4 v160, v[40:43], s[98:99] nt
	s_waitcnt lgkmcnt(0)
; __device__ __forceinline__ u32x4 pack8(const float (&f)[8]) { u32x4 w; w.x = cvt_pk_bf16(f[0], f[1]); w.y = cvt_pk_bf16(f[2], f[3]); w.z = cvt_pk_bf16(f[4], f[5]); w.w = cvt_pk_bf16(f[6], f[7]); return w; }
; __device__ __forceinline__ float sigm(float x) { return __builtin_amdgcn_rcpf(1.f + __builtin_amdgcn_exp2f(-1.4426950408889634f * x)); }
;     __device__ __forceinline__ void operator()(const f32x4 (&acc)[2][2][4][2], const Unit& u, int wr, int wc, int fr, int fq) const {
;     ...
;                     } else if (act == 2) {
; #pragma unroll
;                         for (int e = 0; e < 8; ++e) f[e] = f[e] * sigm(f[e]);
;                     }
;                     __builtin_nontemporal_store(pack8(f), (u32x4*)(rowp + bj * HALF)); } }
	global_store_dwordx4 v160, v[32:35], s[98:99] offset:256 nt
	v_pk_mul_f32 v[234:235], v[28:29], v[230:231]
	v_pk_mul_f32 v[236:237], v[30:31], v[230:231]
	v_pk_mul_f32 v[238:239], v[24:25], v[230:231]
	v_pk_mul_f32 v[240:241], v[26:27], v[230:231]
	v_exp_f32_e32 v234, v234
	v_exp_f32_e32 v235, v235
	v_exp_f32_e32 v236, v236
	v_exp_f32_e32 v237, v237
	v_exp_f32_e32 v238, v238
	v_exp_f32_e32 v239, v239
	v_exp_f32_e32 v240, v240
	v_exp_f32_e32 v241, v241
	v_pk_add_f32 v[234:235], v[234:235], v[232:233]
	v_pk_add_f32 v[236:237], v[236:237], v[232:233]
	v_pk_add_f32 v[238:239], v[238:239], v[232:233]
	v_pk_add_f32 v[240:241], v[240:241], v[232:233]
	v_rcp_f32_e32 v234, v234
	v_rcp_f32_e32 v235, v235
	v_rcp_f32_e32 v236, v236
	v_rcp_f32_e32 v237, v237
	v_rcp_f32_e32 v238, v238
	v_rcp_f32_e32 v239, v239
	v_rcp_f32_e32 v240, v240
	v_rcp_f32_e32 v241, v241
	v_pk_mul_f32 v[234:235], v[28:29], v[234:235]
	v_pk_mul_f32 v[236:237], v[30:31], v[236:237]
	v_pk_mul_f32 v[238:239], v[24:25], v[238:239]
	v_pk_mul_f32 v[240:241], v[26:27], v[240:241]
	v_cvt_pk_bf16_f32 v28, v234, v235
	v_cvt_pk_bf16_f32 v29, v236, v237
	v_cvt_pk_bf16_f32 v30, v238, v239
	v_cvt_pk_bf16_f32 v31, v240, v241
	ds_write_b128 v228, v[28:31]
	ds_read_b128 v[24:27], v229
	v_pk_mul_f32 v[234:235], v[20:21], v[230:231]
	v_pk_mul_f32 v[236:237], v[22:23], v[230:231]
	v_pk_mul_f32 v[238:239], v[16:17], v[230:231]
	v_pk_mul_f32 v[240:241], v[18:19], v[230:231]
	v_exp_f32_e32 v234, v234
	v_exp_f32_e32 v235, v235
	v_exp_f32_e32 v236, v236
	v_exp_f32_e32 v237, v237
	v_exp_f32_e32 v238, v238
	v_exp_f32_e32 v239, v239
	v_exp_f32_e32 v240, v240
	v_exp_f32_e32 v241, v241
	v_pk_add_f32 v[234:235], v[234:235], v[232:233]
	v_pk_add_f32 v[236:237], v[236:237], v[232:233]
	v_pk_add_f32 v[238:239], v[238:239], v[232:233]
	v_pk_add_f32 v[240:241], v[240:241], v[232:233]
	v_rcp_f32_e32 v234, v234
	v_rcp_f32_e32 v235, v235
	v_rcp_f32_e32 v236, v236
	v_rcp_f32_e32 v237, v237
	v_rcp_f32_e32 v238, v238
	v_rcp_f32_e32 v239, v239
	v_rcp_f32_e32 v240, v240
	v_rcp_f32_e32 v241, v241
	v_pk_mul_f32 v[234:235], v[20:21], v[234:235]
	v_pk_mul_f32 v[236:237], v[22:23], v[236:237]
	v_pk_mul_f32 v[238:239], v[16:17], v[238:239]
	v_pk_mul_f32 v[240:241], v[18:19], v[240:241]
	v_cvt_pk_bf16_f32 v20, v234, v235
	v_cvt_pk_bf16_f32 v21, v236, v237
	v_cvt_pk_bf16_f32 v22, v238, v239
	v_cvt_pk_bf16_f32 v23, v240, v241
	ds_write_b128 v228, v[20:23]
	ds_read_b128 v[16:19], v229
	v_pk_mul_f32 v[234:235], v[12:13], v[230:231]
	v_pk_mul_f32 v[236:237], v[14:15], v[230:231]
	v_pk_mul_f32 v[238:239], v[8:9], v[230:231]
	v_pk_mul_f32 v[240:241], v[10:11], v[230:231]
	v_exp_f32_e32 v234, v234
	v_exp_f32_e32 v235, v235
	v_exp_f32_e32 v236, v236
	v_exp_f32_e32 v237, v237
	v_exp_f32_e32 v238, v238
	v_exp_f32_e32 v239, v239
	v_exp_f32_e32 v240, v240
	v_exp_f32_e32 v241, v241
	v_pk_add_f32 v[234:235], v[234:235], v[232:233]
	v_pk_add_f32 v[236:237], v[236:237], v[232:233]
	v_pk_add_f32 v[238:239], v[238:239], v[232:233]
	v_pk_add_f32 v[240:241], v[240:241], v[232:233]
	v_rcp_f32_e32 v234, v234
	v_rcp_f32_e32 v235, v235
	v_rcp_f32_e32 v236, v236
	v_rcp_f32_e32 v237, v237
	v_rcp_f32_e32 v238, v238
	v_rcp_f32_e32 v239, v239
	v_rcp_f32_e32 v240, v240
	v_rcp_f32_e32 v241, v241
	v_pk_mul_f32 v[234:235], v[12:13], v[234:235]
	v_pk_mul_f32 v[236:237], v[14:15], v[236:237]
	v_pk_mul_f32 v[238:239], v[8:9], v[238:239]
	v_pk_mul_f32 v[240:241], v[10:11], v[240:241]
	v_cvt_pk_bf16_f32 v12, v234, v235
	v_cvt_pk_bf16_f32 v13, v236, v237
	v_cvt_pk_bf16_f32 v14, v238, v239
	v_cvt_pk_bf16_f32 v15, v240, v241
	ds_write_b128 v228, v[12:15]
	ds_read_b128 v[8:11], v229
	v_pk_mul_f32 v[234:235], v[4:5], v[230:231]
	v_pk_mul_f32 v[236:237], v[6:7], v[230:231]
	v_pk_mul_f32 v[238:239], v[0:1], v[230:231]
	v_pk_mul_f32 v[240:241], v[2:3], v[230:231]
	v_exp_f32_e32 v234, v234
	v_exp_f32_e32 v235, v235
	v_exp_f32_e32 v236, v236
	v_exp_f32_e32 v237, v237
	v_exp_f32_e32 v238, v238
	v_exp_f32_e32 v239, v239
	v_exp_f32_e32 v240, v240
	v_exp_f32_e32 v241, v241
	v_pk_add_f32 v[234:235], v[234:235], v[232:233]
	v_pk_add_f32 v[236:237], v[236:237], v[232:233]
	v_pk_add_f32 v[238:239], v[238:239], v[232:233]
	v_pk_add_f32 v[240:241], v[240:241], v[232:233]
	v_rcp_f32_e32 v234, v234
	v_rcp_f32_e32 v235, v235
	v_rcp_f32_e32 v236, v236
	v_rcp_f32_e32 v237, v237
	v_rcp_f32_e32 v238, v238
	v_rcp_f32_e32 v239, v239
	v_rcp_f32_e32 v240, v240
	v_rcp_f32_e32 v241, v241
	v_pk_mul_f32 v[234:235], v[4:5], v[234:235]
	v_pk_mul_f32 v[236:237], v[6:7], v[236:237]
	v_pk_mul_f32 v[238:239], v[0:1], v[238:239]
	v_pk_mul_f32 v[240:241], v[2:3], v[240:241]
	v_cvt_pk_bf16_f32 v4, v234, v235
	v_cvt_pk_bf16_f32 v5, v236, v237
	v_cvt_pk_bf16_f32 v6, v238, v239
	v_cvt_pk_bf16_f32 v7, v240, v241
	ds_write_b128 v228, v[4:7]
	ds_read_b128 v[0:3], v229
	v_add_u32_e32 v160, s100, v160
	s_waitcnt lgkmcnt(6)
	global_store_dwordx4 v160, v[24:27], s[98:99] nt
	s_waitcnt lgkmcnt(4)
	global_store_dwordx4 v160, v[16:19], s[98:99] offset:256 nt
	v_add_u32_e32 v160, s100, v160
	s_waitcnt lgkmcnt(2)
	global_store_dwordx4 v160, v[8:11], s[98:99] nt
	s_waitcnt lgkmcnt(0)
	global_store_dwordx4 v160, v[0:3], s[98:99] offset:256 nt
	s_andn2_b64 vcc, exec, s[0:1]
	s_mov_b64 s[0:1], -1
	s_branch .Lp1_tail
; __device__ __forceinline__ u32x4 pack8(const float (&f)[8]) { u32x4 w; w.x = cvt_pk_bf16(f[0], f[1]); w.y = cvt_pk_bf16(f[2], f[3]); w.z = cvt_pk_bf16(f[4], f[5]); w.w = cvt_pk_bf16(f[6], f[7]); return w; }
; __device__ __forceinline__ float sigm(float x) { return __builtin_amdgcn_rcpf(1.f + __builtin_amdgcn_exp2f(-1.4426950408889634f * x)); }
;     __device__ __forceinline__ void operator()(const f32x4 (&acc)[2][2][4][2], const Unit& u, int wr, int wc, int fr, int fq) const {
;     ...
;                     if (act == 1) {
; #pragma unroll
;                         for (int e = 0; e < 8; ++e) f[e] = sigm(f[e]);
;     ...
;                     __builtin_nontemporal_store(pack8(f), (u32x4*)(rowp + bj * HALF)); } }
.Lp1_sig:
	v_lshl_add_u32 v160, s6, 8, v154
	v_add_u32_e32 v136, s3, v156
	s_add_u32 s98, s68, s80
	s_addc_u32 s99, s69, s81
	s_lshl_b32 s100, s78, 1
	v_mul_lo_u32 v160, v160, s100
	s_lshl_b32 s100, s78, 5
	v_lshl_add_u32 v160, v136, 1, v160
	v_mov_b32_e32 v230, 0xbfb8aa3b
	v_mov_b32_e32 v231, 0xbfb8aa3b
	v_mov_b32_e32 v232, 1.0
	v_mov_b32_e32 v233, 1.0
	v_pk_mul_f32 v[234:235], v[124:125], v[230:231]
	v_pk_mul_f32 v[236:237], v[126:127], v[230:231]
	v_pk_mul_f32 v[238:239], v[120:121], v[230:231]
	v_pk_mul_f32 v[240:241], v[122:123], v[230:231]
	v_exp_f32_e32 v234, v234
	v_exp_f32_e32 v235, v235
	v_exp_f32_e32 v236, v236
	v_exp_f32_e32 v237, v237
	v_exp_f32_e32 v238, v238
	v_exp_f32_e32 v239, v239
	v_exp_f32_e32 v240, v240
	v_exp_f32_e32 v241, v241
	v_pk_add_f32 v[234:235], v[234:235], v[232:233]
	v_pk_add_f32 v[236:237], v[236:237], v[232:233]
	v_pk_add_f32 v[238:239], v[238:239], v[232:233]
	v_pk_add_f32 v[240:241], v[240:241], v[232:233]
	v_rcp_f32_e32 v234, v234
	v_rcp_f32_e32 v235, v235
	v_rcp_f32_e32 v236, v236
	v_rcp_f32_e32 v237, v237
	v_rcp_f32_e32 v238, v238
	v_rcp_f32_e32 v239, v239
	v_rcp_f32_e32 v240, v240
	v_rcp_f32_e32 v241, v241
	s_nop 0
	v_cvt_pk_bf16_f32 v124, v234, v235
	v_cvt_pk_bf16_f32 v125, v236, v237
	v_cvt_pk_bf16_f32 v126, v238, v239
	v_cvt_pk_bf16_f32 v127, v240, v241
	ds_write_b128 v228, v[124:127]
	ds_read_b128 v[120:123], v229
	v_pk_mul_f32 v[234:235], v[116:117], v[230:231]
	v_pk_mul_f32 v[236:237], v[118:119], v[230:231]
	v_pk_mul_f32 v[238:239], v[112:113], v[230:231]
	v_pk_mul_f32 v[240:241], v[114:115], v[230:231]
	v_exp_f32_e32 v234, v234
	v_exp_f32_e32 v235, v235
	v_exp_f32_e32 v236, v236
	v_exp_f32_e32 v237, v237
	v_exp_f32_e32 v238, v238
	v_exp_f32_e32 v239, v239
	v_exp_f32_e32 v240, v240
	v_exp_f32_e32 v241, v241
	v_pk_add_f32 v[234:235], v[234:235], v[232:233]
	v_pk_add_f32 v[236:237], v[236:237], v[232:233]
	v_pk_add_f32 v[238:239], v[238:239], v[232:233]
	v_pk_add_f32 v[240:241], v[240:241], v[232:233]
	v_rcp_f32_e32 v234, v234
	v_rcp_f32_e32 v235, v235
	v_rcp_f32_e32 v236, v236
	v_rcp_f32_e32 v237, v237
	v_rcp_f32_e32 v238, v238
	v_rcp_f32_e32 v239, v239
	v_rcp_f32_e32 v240, v240
	v_rcp_f32_e32 v241, v241
	s_nop 0
	v_cvt_pk_bf16_f32 v116, v234, v235
	v_cvt_pk_bf16_f32 v117, v236, v237
	v_cvt_pk_bf16_f32 v118, v238, v239
	v_cvt_pk_bf16_f32 v119, v240, v241
	ds_write_b128 v228, v[116:119]
	ds_read_b128 v[112:115], v229
	v_pk_mul_f32 v[234:235], v[108:109], v[230:231]
	v_pk_mul_f32 v[236:237], v[110:111], v[230:231]
	v_pk_mul_f32 v[238:239], v[104:105], v[230:231]
	v_pk_mul_f32 v[240:241], v[106:107], v[230:231]
	v_exp_f32_e32 v234, v234
	v_exp_f32_e32 v235, v235
	v_exp_f32_e32 v236, v236
	v_exp_f32_e32 v237, v237
	v_exp_f32_e32 v238, v238
	v_exp_f32_e32 v239, v239
	v_exp_f32_e32 v240, v240
	v_exp_f32_e32 v241, v241
	v_pk_add_f32 v[234:235], v[234:235], v[232:233]
	v_pk_add_f32 v[236:237], v[236:237], v[232:233]
	v_pk_add_f32 v[238:239], v[238:239], v[232:233]
	v_pk_add_f32 v[240:241], v[240:241], v[232:233]
	v_rcp_f32_e32 v234, v234
	v_rcp_f32_e32 v235, v235
	v_rcp_f32_e32 v236, v236
	v_rcp_f32_e32 v237, v237
	v_rcp_f32_e32 v238, v238
	v_rcp_f32_e32 v239, v239
	v_rcp_f32_e32 v240, v240
	v_rcp_f32_e32 v241, v241
	s_nop 0
	v_cvt_pk_bf16_f32 v108, v234, v235
	v_cvt_pk_bf16_f32 v109, v236, v237
	v_cvt_pk_bf16_f32 v110, v238, v239
	v_cvt_pk_bf16_f32 v111, v240, v241
	ds_write_b128 v228, v[108:111]
	ds_read_b128 v[104:107], v229
	v_pk_mul_f32 v[234:235], v[100:101], v[230:231]
	v_pk_mul_f32 v[236:237], v[102:103], v[230:231]
	v_pk_mul_f32 v[238:239], v[96:97], v[230:231]
	v_pk_mul_f32 v[240:241], v[98:99], v[230:231]
	v_exp_f32_e32 v234, v234
	v_exp_f32_e32 v235, v235
	v_exp_f32_e32 v236, v236
	v_exp_f32_e32 v237, v237
	v_exp_f32_e32 v238, v238
	v_exp_f32_e32 v239, v239
	v_exp_f32_e32 v240, v240
	v_exp_f32_e32 v241, v241
	v_pk_add_f32 v[234:235], v[234:235], v[232:233]
	v_pk_add_f32 v[236:237], v[236:237], v[232:233]
	v_pk_add_f32 v[238:239], v[238:239], v[232:233]
	v_pk_add_f32 v[240:241], v[240:241], v[232:233]
	v_rcp_f32_e32 v234, v234
	v_rcp_f32_e32 v235, v235
	v_rcp_f32_e32 v236, v236
	v_rcp_f32_e32 v237, v237
	v_rcp_f32_e32 v238, v238
	v_rcp_f32_e32 v239, v239
	v_rcp_f32_e32 v240, v240
	v_rcp_f32_e32 v241, v241
	s_nop 0
	v_cvt_pk_bf16_f32 v100, v234, v235
	v_cvt_pk_bf16_f32 v101, v236, v237
	v_cvt_pk_bf16_f32 v102, v238, v239
	v_cvt_pk_bf16_f32 v103, v240, v241
	ds_write_b128 v228, v[100:103]
	ds_read_b128 v[96:99], v229
	s_waitcnt lgkmcnt(6)
	global_store_dwordx4 v160, v[120:123], s[98:99] nt
	s_waitcnt lgkmcnt(4)
	global_store_dwordx4 v160, v[112:115], s[98:99] offset:256 nt
	v_add_u32_e32 v160, s100, v160
	s_waitcnt lgkmcnt(2)
	global_store_dwordx4 v160, v[104:107], s[98:99] nt
	s_waitcnt lgkmcnt(0)
; __device__ __forceinline__ u32x4 pack8(const float (&f)[8]) { u32x4 w; w.x = cvt_pk_bf16(f[0], f[1]); w.y = cvt_pk_bf16(f[2], f[3]); w.z = cvt_pk_bf16(f[4], f[5]); w.w = cvt_pk_bf16(f[6], f[7]); return w; }
; __device__ __forceinline__ float sigm(float x) { return __builtin_amdgcn_rcpf(1.f + __builtin_amdgcn_exp2f(-1.4426950408889634f * x)); }
;     __device__ __forceinline__ void operator()(const f32x4 (&acc)[2][2][4][2], const Unit& u, int wr, int wc, int fr, int fq) const {
;     ...
;                     if (act == 1) {
; #pragma unroll
;                         for (int e = 0; e < 8; ++e) f[e] = sigm(f[e]);
;     ...
;                     __builtin_nontemporal_store(pack8(f), (u32x4*)(rowp + bj * HALF)); } }
	global_store_dwordx4 v160, v[96:99], s[98:99] offset:256 nt
	v_pk_mul_f32 v[234:235], v[92:93], v[230:231]
	v_pk_mul_f32 v[236:237], v[94:95], v[230:231]
	v_pk_mul_f32 v[238:239], v[88:89], v[230:231]
	v_pk_mul_f32 v[240:241], v[90:91], v[230:231]
	v_exp_f32_e32 v234, v234
	v_exp_f32_e32 v235, v235
	v_exp_f32_e32 v236, v236
	v_exp_f32_e32 v237, v237
	v_exp_f32_e32 v238, v238
	v_exp_f32_e32 v239, v239
	v_exp_f32_e32 v240, v240
	v_exp_f32_e32 v241, v241
	v_pk_add_f32 v[234:235], v[234:235], v[232:233]
	v_pk_add_f32 v[236:237], v[236:237], v[232:233]
	v_pk_add_f32 v[238:239], v[238:239], v[232:233]
	v_pk_add_f32 v[240:241], v[240:241], v[232:233]
	v_rcp_f32_e32 v234, v234
	v_rcp_f32_e32 v235, v235
	v_rcp_f32_e32 v236, v236
	v_rcp_f32_e32 v237, v237
	v_rcp_f32_e32 v238, v238
	v_rcp_f32_e32 v239, v239
	v_rcp_f32_e32 v240, v240
	v_rcp_f32_e32 v241, v241
	s_nop 0
	v_cvt_pk_bf16_f32 v92, v234, v235
	v_cvt_pk_bf16_f32 v93, v236, v237
	v_cvt_pk_bf16_f32 v94, v238, v239
	v_cvt_pk_bf16_f32 v95, v240, v241
	ds_write_b128 v228, v[92:95]
	ds_read_b128 v[88:91], v229
	v_pk_mul_f32 v[234:235], v[84:85], v[230:231]
	v_pk_mul_f32 v[236:237], v[86:87], v[230:231]
	v_pk_mul_f32 v[238:239], v[80:81], v[230:231]
	v_pk_mul_f32 v[240:241], v[82:83], v[230:231]
	v_exp_f32_e32 v234, v234
	v_exp_f32_e32 v235, v235
	v_exp_f32_e32 v236, v236
	v_exp_f32_e32 v237, v237
	v_exp_f32_e32 v238, v238
	v_exp_f32_e32 v239, v239
	v_exp_f32_e32 v240, v240
	v_exp_f32_e32 v241, v241
	v_pk_add_f32 v[234:235], v[234:235], v[232:233]
	v_pk_add_f32 v[236:237], v[236:237], v[232:233]
	v_pk_add_f32 v[238:239], v[238:239], v[232:233]
	v_pk_add_f32 v[240:241], v[240:241], v[232:233]
	v_rcp_f32_e32 v234, v234
	v_rcp_f32_e32 v235, v235
	v_rcp_f32_e32 v236, v236
	v_rcp_f32_e32 v237, v237
	v_rcp_f32_e32 v238, v238
	v_rcp_f32_e32 v239, v239
	v_rcp_f32_e32 v240, v240
	v_rcp_f32_e32 v241, v241
	s_nop 0
	v_cvt_pk_bf16_f32 v84, v234, v235
	v_cvt_pk_bf16_f32 v85, v236, v237
	v_cvt_pk_bf16_f32 v86, v238, v239
	v_cvt_pk_bf16_f32 v87, v240, v241
	ds_write_b128 v228, v[84:87]
	ds_read_b128 v[80:83], v229
	v_pk_mul_f32 v[234:235], v[76:77], v[230:231]
	v_pk_mul_f32 v[236:237], v[78:79], v[230:231]
	v_pk_mul_f32 v[238:239], v[72:73], v[230:231]
	v_pk_mul_f32 v[240:241], v[74:75], v[230:231]
	v_exp_f32_e32 v234, v234
	v_exp_f32_e32 v235, v235
	v_exp_f32_e32 v236, v236
	v_exp_f32_e32 v237, v237
	v_exp_f32_e32 v238, v238
	v_exp_f32_e32 v239, v239
	v_exp_f32_e32 v240, v240
	v_exp_f32_e32 v241, v241
	v_pk_add_f32 v[234:235], v[234:235], v[232:233]
	v_pk_add_f32 v[236:237], v[236:237], v[232:233]
	v_pk_add_f32 v[238:239], v[238:239], v[232:233]
	v_pk_add_f32 v[240:241], v[240:241], v[232:233]
	v_rcp_f32_e32 v234, v234
	v_rcp_f32_e32 v235, v235
	v_rcp_f32_e32 v236, v236
	v_rcp_f32_e32 v237, v237
	v_rcp_f32_e32 v238, v238
	v_rcp_f32_e32 v239, v239
	v_rcp_f32_e32 v240, v240
	v_rcp_f32_e32 v241, v241
	s_nop 0
	v_cvt_pk_bf16_f32 v76, v234, v235
	v_cvt_pk_bf16_f32 v77, v236, v237
	v_cvt_pk_bf16_f32 v78, v238, v239
	v_cvt_pk_bf16_f32 v79, v240, v241
	ds_write_b128 v228, v[76:79]
	ds_read_b128 v[72:75], v229
	v_pk_mul_f32 v[234:235], v[68:69], v[230:231]
	v_pk_mul_f32 v[236:237], v[70:71], v[230:231]
	v_pk_mul_f32 v[238:239], v[64:65], v[230:231]
	v_pk_mul_f32 v[240:241], v[66:67], v[230:231]
	v_exp_f32_e32 v234, v234
	v_exp_f32_e32 v235, v235
	v_exp_f32_e32 v236, v236
	v_exp_f32_e32 v237, v237
	v_exp_f32_e32 v238, v238
	v_exp_f32_e32 v239, v239
	v_exp_f32_e32 v240, v240
	v_exp_f32_e32 v241, v241
	v_pk_add_f32 v[234:235], v[234:235], v[232:233]
	v_pk_add_f32 v[236:237], v[236:237], v[232:233]
	v_pk_add_f32 v[238:239], v[238:239], v[232:233]
	v_pk_add_f32 v[240:241], v[240:241], v[232:233]
	v_rcp_f32_e32 v234, v234
	v_rcp_f32_e32 v235, v235
	v_rcp_f32_e32 v236, v236
	v_rcp_f32_e32 v237, v237
	v_rcp_f32_e32 v238, v238
	v_rcp_f32_e32 v239, v239
	v_rcp_f32_e32 v240, v240
	v_rcp_f32_e32 v241, v241
	s_nop 0
	v_cvt_pk_bf16_f32 v68, v234, v235
	v_cvt_pk_bf16_f32 v69, v236, v237
	v_cvt_pk_bf16_f32 v70, v238, v239
	v_cvt_pk_bf16_f32 v71, v240, v241
	ds_write_b128 v228, v[68:71]
	ds_read_b128 v[64:67], v229
	v_add_u32_e32 v160, s100, v160
	s_waitcnt lgkmcnt(6)
	global_store_dwordx4 v160, v[88:91], s[98:99] nt
	s_waitcnt lgkmcnt(4)
	global_store_dwordx4 v160, v[80:83], s[98:99] offset:256 nt
	v_add_u32_e32 v160, s100, v160
	s_waitcnt lgkmcnt(2)
	global_store_dwordx4 v160, v[72:75], s[98:99] nt
	s_waitcnt lgkmcnt(0)
; __device__ __forceinline__ u32x4 pack8(const float (&f)[8]) { u32x4 w; w.x = cvt_pk_bf16(f[0], f[1]); w.y = cvt_pk_bf16(f[2], f[3]); w.z = cvt_pk_bf16(f[4], f[5]); w.w = cvt_pk_bf16(f[6], f[7]); return w; }
; __device__ __forceinline__ float sigm(float x) { return __builtin_amdgcn_rcpf(1.f + __builtin_amdgcn_exp2f(-1.4426950408889634f * x)); }
;     __device__ __forceinline__ void operator()(const f32x4 (&acc)[2][2][4][2], const Unit& u, int wr, int wc, int fr, int fq) const {
;     ...
;                     if (act == 1) {
; #pragma unroll
;                         for (int e = 0; e < 8; ++e) f[e] = sigm(f[e]);
;     ...
;                     __builtin_nontemporal_store(pack8(f), (u32x4*)(rowp + bj * HALF)); } }
	global_store_dwordx4 v160, v[64:67], s[98:99] offset:256 nt
	v_pk_mul_f32 v[234:235], v[60:61], v[230:231]
	v_pk_mul_f32 v[236:237], v[62:63], v[230:231]
	v_pk_mul_f32 v[238:239], v[56:57], v[230:231]
	v_pk_mul_f32 v[240:241], v[58:59], v[230:231]
	v_exp_f32_e32 v234, v234
	v_exp_f32_e32 v235, v235
	v_exp_f32_e32 v236, v236
	v_exp_f32_e32 v237, v237
	v_exp_f32_e32 v238, v238
	v_exp_f32_e32 v239, v239
	v_exp_f32_e32 v240, v240
	v_exp_f32_e32 v241, v241
	v_pk_add_f32 v[234:235], v[234:235], v[232:233]
	v_pk_add_f32 v[236:237], v[236:237], v[232:233]
	v_pk_add_f32 v[238:239], v[238:239], v[232:233]
	v_pk_add_f32 v[240:241], v[240:241], v[232:233]
	v_rcp_f32_e32 v234, v234
	v_rcp_f32_e32 v235, v235
	v_rcp_f32_e32 v236, v236
	v_rcp_f32_e32 v237, v237
	v_rcp_f32_e32 v238, v238
	v_rcp_f32_e32 v239, v239
	v_rcp_f32_e32 v240, v240
	v_rcp_f32_e32 v241, v241
	s_nop 0
	v_cvt_pk_bf16_f32 v60, v234, v235
	v_cvt_pk_bf16_f32 v61, v236, v237
	v_cvt_pk_bf16_f32 v62, v238, v239
	v_cvt_pk_bf16_f32 v63, v240, v241
	ds_write_b128 v228, v[60:63]
	ds_read_b128 v[56:59], v229
	v_pk_mul_f32 v[234:235], v[52:53], v[230:231]
	v_pk_mul_f32 v[236:237], v[54:55], v[230:231]
	v_pk_mul_f32 v[238:239], v[48:49], v[230:231]
	v_pk_mul_f32 v[240:241], v[50:51], v[230:231]
	v_exp_f32_e32 v234, v234
	v_exp_f32_e32 v235, v235
	v_exp_f32_e32 v236, v236
	v_exp_f32_e32 v237, v237
	v_exp_f32_e32 v238, v238
	v_exp_f32_e32 v239, v239
	v_exp_f32_e32 v240, v240
	v_exp_f32_e32 v241, v241
	v_pk_add_f32 v[234:235], v[234:235], v[232:233]
	v_pk_add_f32 v[236:237], v[236:237], v[232:233]
	v_pk_add_f32 v[238:239], v[238:239], v[232:233]
	v_pk_add_f32 v[240:241], v[240:241], v[232:233]
	v_rcp_f32_e32 v234, v234
	v_rcp_f32_e32 v235, v235
	v_rcp_f32_e32 v236, v236
	v_rcp_f32_e32 v237, v237
	v_rcp_f32_e32 v238, v238
	v_rcp_f32_e32 v239, v239
	v_rcp_f32_e32 v240, v240
	v_rcp_f32_e32 v241, v241
	s_nop 0
	v_cvt_pk_bf16_f32 v52, v234, v235
	v_cvt_pk_bf16_f32 v53, v236, v237
	v_cvt_pk_bf16_f32 v54, v238, v239
	v_cvt_pk_bf16_f32 v55, v240, v241
	ds_write_b128 v228, v[52:55]
	ds_read_b128 v[48:51], v229
	v_pk_mul_f32 v[234:235], v[44:45], v[230:231]
	v_pk_mul_f32 v[236:237], v[46:47], v[230:231]
	v_pk_mul_f32 v[238:239], v[40:41], v[230:231]
	v_pk_mul_f32 v[240:241], v[42:43], v[230:231]
	v_exp_f32_e32 v234, v234
	v_exp_f32_e32 v235, v235
	v_exp_f32_e32 v236, v236
	v_exp_f32_e32 v237, v237
	v_exp_f32_e32 v238, v238
	v_exp_f32_e32 v239, v239
	v_exp_f32_e32 v240, v240
	v_exp_f32_e32 v241, v241
	v_pk_add_f32 v[234:235], v[234:235], v[232:233]
	v_pk_add_f32 v[236:237], v[236:237], v[232:233]
	v_pk_add_f32 v[238:239], v[238:239], v[232:233]
	v_pk_add_f32 v[240:241], v[240:241], v[232:233]
	v_rcp_f32_e32 v234, v234
	v_rcp_f32_e32 v235, v235
	v_rcp_f32_e32 v236, v236
	v_rcp_f32_e32 v237, v237
	v_rcp_f32_e32 v238, v238
	v_rcp_f32_e32 v239, v239
	v_rcp_f32_e32 v240, v240
	v_rcp_f32_e32 v241, v241
	s_nop 0
	v_cvt_pk_bf16_f32 v44, v234, v235
	v_cvt_pk_bf16_f32 v45, v236, v237
	v_cvt_pk_bf16_f32 v46, v238, v239
	v_cvt_pk_bf16_f32 v47, v240, v241
	ds_write_b128 v228, v[44:47]
	ds_read_b128 v[40:43], v229
	v_pk_mul_f32 v[234:235], v[36:37], v[230:231]
	v_pk_mul_f32 v[236:237], v[38:39], v[230:231]
	v_pk_mul_f32 v[238:239], v[32:33], v[230:231]
	v_pk_mul_f32 v[240:241], v[34:35], v[230:231]
	v_exp_f32_e32 v234, v234
	v_exp_f32_e32 v235, v235
	v_exp_f32_e32 v236, v236
	v_exp_f32_e32 v237, v237
	v_exp_f32_e32 v238, v238
	v_exp_f32_e32 v239, v239
	v_exp_f32_e32 v240, v240
	v_exp_f32_e32 v241, v241
	v_pk_add_f32 v[234:235], v[234:235], v[232:233]
	v_pk_add_f32 v[236:237], v[236:237], v[232:233]
	v_pk_add_f32 v[238:239], v[238:239], v[232:233]
	v_pk_add_f32 v[240:241], v[240:241], v[232:233]
	v_rcp_f32_e32 v234, v234
	v_rcp_f32_e32 v235, v235
	v_rcp_f32_e32 v236, v236
	v_rcp_f32_e32 v237, v237
	v_rcp_f32_e32 v238, v238
	v_rcp_f32_e32 v239, v239
	v_rcp_f32_e32 v240, v240
	v_rcp_f32_e32 v241, v241
	s_nop 0
	v_cvt_pk_bf16_f32 v36, v234, v235
	v_cvt_pk_bf16_f32 v37, v236, v237
	v_cvt_pk_bf16_f32 v38, v238, v239
	v_cvt_pk_bf16_f32 v39, v240, v241
	ds_write_b128 v228, v[36:39]
	ds_read_b128 v[32:35], v229
	v_mad_u32_u24 v160, s100, 5, v160
	s_waitcnt lgkmcnt(6)
	global_store_dwordx4 v160, v[56:59], s[98:99] nt
	s_waitcnt lgkmcnt(4)
	global_store_dwordx4 v160, v[48:51], s[98:99] offset:256 nt
	v_add_u32_e32 v160, s100, v160
	s_waitcnt lgkmcnt(2)
	global_store_dwordx4 v160, v[40:43], s[98:99] nt
	s_waitcnt lgkmcnt(0)
; __device__ __forceinline__ u32x4 pack8(const float (&f)[8]) { u32x4 w; w.x = cvt_pk_bf16(f[0], f[1]); w.y = cvt_pk_bf16(f[2], f[3]); w.z = cvt_pk_bf16(f[4], f[5]); w.w = cvt_pk_bf16(f[6], f[7]); return w; }
; __device__ __forceinline__ float sigm(float x) { return __builtin_amdgcn_rcpf(1.f + __builtin_amdgcn_exp2f(-1.4426950408889634f * x)); }
;     __device__ __forceinline__ void operator()(const f32x4 (&acc)[2][2][4][2], const Unit& u, int wr, int wc, int fr, int fq) const {
;     ...
;                     if (act == 1) {
; #pragma unroll
;                         for (int e = 0; e < 8; ++e) f[e] = sigm(f[e]);
;     ...
;                     __builtin_nontemporal_store(pack8(f), (u32x4*)(rowp + bj * HALF)); } }
	global_store_dwordx4 v160, v[32:35], s[98:99] offset:256 nt
	v_pk_mul_f32 v[234:235], v[28:29], v[230:231]
	v_pk_mul_f32 v[236:237], v[30:31], v[230:231]
	v_pk_mul_f32 v[238:239], v[24:25], v[230:231]
	v_pk_mul_f32 v[240:241], v[26:27], v[230:231]
	v_exp_f32_e32 v234, v234
	v_exp_f32_e32 v235, v235
	v_exp_f32_e32 v236, v236
	v_exp_f32_e32 v237, v237
	v_exp_f32_e32 v238, v238
	v_exp_f32_e32 v239, v239
	v_exp_f32_e32 v240, v240
	v_exp_f32_e32 v241, v241
	v_pk_add_f32 v[234:235], v[234:235], v[232:233]
	v_pk_add_f32 v[236:237], v[236:237], v[232:233]
	v_pk_add_f32 v[238:239], v[238:239], v[232:233]
	v_pk_add_f32 v[240:241], v[240:241], v[232:233]
	v_rcp_f32_e32 v234, v234
	v_rcp_f32_e32 v235, v235
	v_rcp_f32_e32 v236, v236
	v_rcp_f32_e32 v237, v237
	v_rcp_f32_e32 v238, v238
	v_rcp_f32_e32 v239, v239
	v_rcp_f32_e32 v240, v240
	v_rcp_f32_e32 v241, v241
	s_nop 0
	v_cvt_pk_bf16_f32 v28, v234, v235
	v_cvt_pk_bf16_f32 v29, v236, v237
	v_cvt_pk_bf16_f32 v30, v238, v239
	v_cvt_pk_bf16_f32 v31, v240, v241
	ds_write_b128 v228, v[28:31]
	ds_read_b128 v[24:27], v229
	v_pk_mul_f32 v[234:235], v[20:21], v[230:231]
	v_pk_mul_f32 v[236:237], v[22:23], v[230:231]
	v_pk_mul_f32 v[238:239], v[16:17], v[230:231]
	v_pk_mul_f32 v[240:241], v[18:19], v[230:231]
	v_exp_f32_e32 v234, v234
	v_exp_f32_e32 v235, v235
	v_exp_f32_e32 v236, v236
	v_exp_f32_e32 v237, v237
	v_exp_f32_e32 v238, v238
	v_exp_f32_e32 v239, v239
	v_exp_f32_e32 v240, v240
	v_exp_f32_e32 v241, v241
	v_pk_add_f32 v[234:235], v[234:235], v[232:233]
	v_pk_add_f32 v[236:237], v[236:237], v[232:233]
	v_pk_add_f32 v[238:239], v[238:239], v[232:233]
	v_pk_add_f32 v[240:241], v[240:241], v[232:233]
	v_rcp_f32_e32 v234, v234
	v_rcp_f32_e32 v235, v235
	v_rcp_f32_e32 v236, v236
	v_rcp_f32_e32 v237, v237
	v_rcp_f32_e32 v238, v238
	v_rcp_f32_e32 v239, v239
	v_rcp_f32_e32 v240, v240
	v_rcp_f32_e32 v241, v241
	s_nop 0
	v_cvt_pk_bf16_f32 v20, v234, v235
	v_cvt_pk_bf16_f32 v21, v236, v237
	v_cvt_pk_bf16_f32 v22, v238, v239
	v_cvt_pk_bf16_f32 v23, v240, v241
	ds_write_b128 v228, v[20:23]
	ds_read_b128 v[16:19], v229
	v_pk_mul_f32 v[234:235], v[12:13], v[230:231]
	v_pk_mul_f32 v[236:237], v[14:15], v[230:231]
	v_pk_mul_f32 v[238:239], v[8:9], v[230:231]
	v_pk_mul_f32 v[240:241], v[10:11], v[230:231]
	v_exp_f32_e32 v234, v234
	v_exp_f32_e32 v235, v235
	v_exp_f32_e32 v236, v236
	v_exp_f32_e32 v237, v237
	v_exp_f32_e32 v238, v238
	v_exp_f32_e32 v239, v239
	v_exp_f32_e32 v240, v240
	v_exp_f32_e32 v241, v241
	v_pk_add_f32 v[234:235], v[234:235], v[232:233]
	v_pk_add_f32 v[236:237], v[236:237], v[232:233]
	v_pk_add_f32 v[238:239], v[238:239], v[232:233]
	v_pk_add_f32 v[240:241], v[240:241], v[232:233]
	v_rcp_f32_e32 v234, v234
	v_rcp_f32_e32 v235, v235
	v_rcp_f32_e32 v236, v236
	v_rcp_f32_e32 v237, v237
	v_rcp_f32_e32 v238, v238
	v_rcp_f32_e32 v239, v239
	v_rcp_f32_e32 v240, v240
	v_rcp_f32_e32 v241, v241
	s_nop 0
	v_cvt_pk_bf16_f32 v12, v234, v235
	v_cvt_pk_bf16_f32 v13, v236, v237
	v_cvt_pk_bf16_f32 v14, v238, v239
	v_cvt_pk_bf16_f32 v15, v240, v241
	ds_write_b128 v228, v[12:15]
	ds_read_b128 v[8:11], v229
	v_pk_mul_f32 v[234:235], v[4:5], v[230:231]
	v_pk_mul_f32 v[236:237], v[6:7], v[230:231]
	v_pk_mul_f32 v[238:239], v[0:1], v[230:231]
	v_pk_mul_f32 v[240:241], v[2:3], v[230:231]
	v_exp_f32_e32 v234, v234
	v_exp_f32_e32 v235, v235
	v_exp_f32_e32 v236, v236
	v_exp_f32_e32 v237, v237
	v_exp_f32_e32 v238, v238
	v_exp_f32_e32 v239, v239
	v_exp_f32_e32 v240, v240
	v_exp_f32_e32 v241, v241
	v_pk_add_f32 v[234:235], v[234:235], v[232:233]
	v_pk_add_f32 v[236:237], v[236:237], v[232:233]
	v_pk_add_f32 v[238:239], v[238:239], v[232:233]
	v_pk_add_f32 v[240:241], v[240:241], v[232:233]
	v_rcp_f32_e32 v234, v234
	v_rcp_f32_e32 v235, v235
	v_rcp_f32_e32 v236, v236
	v_rcp_f32_e32 v237, v237
	v_rcp_f32_e32 v238, v238
	v_rcp_f32_e32 v239, v239
	v_rcp_f32_e32 v240, v240
	v_rcp_f32_e32 v241, v241
	s_nop 0
	v_cvt_pk_bf16_f32 v4, v234, v235
	v_cvt_pk_bf16_f32 v5, v236, v237
	v_cvt_pk_bf16_f32 v6, v238, v239
	v_cvt_pk_bf16_f32 v7, v240, v241
	ds_write_b128 v228, v[4:7]
	ds_read_b128 v[0:3], v229
	v_add_u32_e32 v160, s100, v160
	s_waitcnt lgkmcnt(6)
	global_store_dwordx4 v160, v[24:27], s[98:99] nt
	s_waitcnt lgkmcnt(4)
	global_store_dwordx4 v160, v[16:19], s[98:99] offset:256 nt
	v_add_u32_e32 v160, s100, v160
	s_waitcnt lgkmcnt(2)
	global_store_dwordx4 v160, v[8:11], s[98:99] nt
	s_waitcnt lgkmcnt(0)
	global_store_dwordx4 v160, v[0:3], s[98:99] offset:256 nt
	s_andn2_b64 vcc, exec, s[0:1]
	s_mov_b64 s[0:1], -1
	s_branch .Lp1_tail

;     __host__ __device__ bool next(int i, Unit& u) const { Unit v; if (!base.next(i >> 1, v)) return false; u.pm = v.pm + ((i & 1) ? 128 : 0); u.pn = v.pn + ((i & 1) ? 4 : 0); return true; }
; #define PG8_WAIT_V(n) asm volatile("s_waitcnt vmcnt(" #n ")" ::: "memory")
; #define PG8_BAR __builtin_amdgcn_s_barrier()
; template <class Epi, class Sched, bool ALIGN_EPI = false, bool SP2 = false>
; __device__ __forceinline__ void gemm_phase(PG8_LAS unsigned char* lds, const Gemm g, const Sched& S, const Epi& E) {
;     int tid_ = threadIdx.x; asm volatile("" : "+v"(tid_));
;     const int tid = tid_, wid = __builtin_amdgcn_readfirstlane(tid >> 6), lane = tid & 63, wr = wid >> 2, wc = wid & 3, fr = lane & 15, fq = lane >> 4;
;     const int K = g.K, nt = K / BK;
;     unsigned voffA[2], voffB[2];
; #pragma unroll
;     for (int i = 0; i < 2; ++i) { int R, C; stage_rc(tid * 16 + i * 8192, R, C); const int Rb = Epi::PERM ? ((R & ~31) + perm32(R & 31)) : R;
;         voffA[i] = (unsigned)(R * K + C) * 2u; voffB[i] = (unsigned)(Rb * K + C) * 2u; }
;     const size_t kstep = (size_t)(BK * 2);
;     const size_t hstep = (size_t)HALF * K * 2;
;     const size_t tstep = 2 * hstep;
;     const unsigned ldsw = (unsigned)wid * 1024u;
;     const int aoff = lds_byte(wr * 64 + fr, fq * 8), boff = lds_byte(wc * 32 + fr, fq * 8);
;     ...
;     Unit cur, nxt; int ui = 0;
;     if (!S.next(0, cur)) return;
;     f32x4 acc[2][2][4][2];
; #pragma unroll
;     for (int a = 0; a < 2; ++a)
; #pragma unroll
;         for (int b = 0; b < 2; ++b)
; #pragma unroll
;             for (int m = 0; m < 4; ++m)
; #pragma unroll
;                 for (int n = 0; n < 2; ++n) acc[a][b][m][n] = (f32x4){0.f, 0.f, 0.f, 0.f};
;     bf16x8 At[4][2], B0[2][2], B1[2][2];
;     const char* cA = (const char*)g.A + (size_t)cur.pm * tstep; const char* cB = (const char*)g.Bt + (size_t)cur.pn * tstep;
;     S.a_ready(cur);
;     if constexpr (SP2) {
;         PG8_STAGE(PG8_SB(0, 0), cB, voffB); PG8_STAGE(PG8_SB(0, 1), cB + hstep, voffB); PG8_STAGE(PG8_SA(0, 0), cA, voffA); PG8_STAGE(PG8_SA(0, 1), cA + hstep, voffA);
;         if (wr == 1) PG8_BAR;
;         PG8_WAIT_V(2); PG8_BAR;
;         PG8_STAGE(PG8_SB(1, 0), cB + kstep, voffB); PG8_STAGE(PG8_SA(1, 0), cA + kstep, voffA); PG8_STAGE(PG8_SB(1, 1), cB + hstep + kstep, voffB);
;         PG8_WAIT_V(6); PG8_BAR;
.LBB0_725:
	s_mov_b32 s98, 0
	s_bfe_u32 s98, s2, 0x20003
	s_cmp_eq_u32 s98, 0
	s_cbranch_scc1 .Lstg5_done
.Lstg5_loop:
	s_sleep 35
	s_sub_u32 s98, s98, 1
	s_cmp_lg_u32 s98, 0
	s_cbranch_scc1 .Lstg5_loop
.Lstg5_done:
	v_ashrrev_i32_e32 v1, 31, v8
	v_lshrrev_b32_e32 v1, 26, v1
	v_add_u32_e32 v1, v8, v1
	v_ashrrev_i32_e32 v9, 6, v1
	v_bfe_i32 v1, v8, 27, 1
	v_lshlrev_b32_e32 v0, 4, v8
	v_lshrrev_b32_e32 v1, 22, v1
	v_add_u32_e32 v1, v0, v1
	v_and_b32_e32 v1, 0xfffffc00, v1
	v_sub_u32_e32 v1, v0, v1
	v_lshrrev_b32_e32 v2, 4, v1
	v_bitop3_b32 v1, v2, v1, 32 bitop3:0x6c
	v_ashrrev_i32_e32 v3, 31, v1
	v_lshrrev_b32_e32 v3, 26, v3
	v_add_u32_e32 v3, v1, v3
	v_lshlrev_b32_e32 v2, 3, v9
	v_ashrrev_i32_e32 v10, 6, v3
	v_and_b32_e32 v3, 0xc0, v3
	v_and_b32_e32 v2, -16, v2
	v_sub_u32_e32 v1, v1, v3
	v_mov_b32_e32 v3, 1
	v_add_u32_e32 v2, v10, v2
	v_ashrrev_i16_sdwa v1, v3, sext(v1) dst_sel:DWORD dst_unused:UNUSED_PAD src0_sel:DWORD src1_sel:BYTE_0
	s_ashr_i32 s4, s3, 3
	v_lshlrev_b32_e32 v4, 5, v9
	v_bfe_i32 v11, v1, 0, 16
	v_lshlrev_b32_e32 v1, 1, v2
	v_lshrrev_b32_e32 v5, 2, v2
	v_and_b32_e32 v6, 3, v10
	s_mov_b32 s3, 0x1fffe0
	v_and_b32_e32 v4, 32, v4
	v_and_b32_e32 v1, 24, v1
	v_and_b32_e32 v5, 4, v5
	v_and_or_b32 v6, v2, s3, v6
	v_or3_b32 v1, v6, v5, v1
	v_add_lshl_u32 v4, v4, v11, 1
	v_add_u32_e32 v0, 0x2000, v0
	v_lshl_add_u32 v130, v1, 11, v4
	v_ashrrev_i32_e32 v1, 31, v0
	s_add_i32 s4, s6, s4
	v_lshrrev_b32_e32 v1, 22, v1
	s_ashr_i32 s6, s4, 31
	v_add_u32_e32 v1, v0, v1
	s_lshr_b32 s6, s6, 25
	v_ashrrev_i32_e32 v12, 10, v1
	s_add_i32 s6, s4, s6
	v_mul_i32_i24_e32 v1, 0x400, v12
	s_ashr_i32 s7, s6, 7
	s_and_b32 s6, s6, 0xffffff80
	v_sub_u32_e32 v0, v0, v1
	s_sub_i32 s6, s4, s6
	v_lshrrev_b32_e32 v1, 4, v0
	s_bfe_i32 s4, s6, 0x80000
	v_bitop3_b32 v0, v1, v0, 32 bitop3:0x6c
	s_bfe_u32 s4, s4, 0x3000c
	v_lshl_add_u32 v128, v2, 11, v4
	v_ashrrev_i32_e32 v2, 31, v0
	s_add_i32 s11, s6, s4
	v_lshrrev_b32_e32 v2, 26, v2
	s_bfe_i32 s4, s11, 0x80000
	s_and_b32 s11, s11, 0xf8
	v_add_u32_e32 v2, v0, v2
	s_sub_i32 s6, s6, s11
	v_lshlrev_b32_e32 v1, 3, v12
	v_ashrrev_i32_e32 v13, 6, v2
	v_and_b32_e32 v2, 0xc0, v2
	s_lshl_b32 s7, s7, 3
	s_sext_i32_i16 s4, s4
	s_sext_i32_i8 s6, s6
	s_ashr_i32 s5, s12, 8
	v_and_b32_e32 v1, -16, v1
	v_sub_u32_e32 v0, v0, v2
	s_lshr_b32 s4, s4, 3
	s_add_i32 s40, s7, s6
	v_add_u32_e32 v1, v13, v1
	v_ashrrev_i16_sdwa v0, v3, sext(v0) dst_sel:DWORD dst_unused:UNUSED_PAD src0_sel:DWORD src1_sel:BYTE_0
	v_and_b32_e32 v3, 3, v13
	s_ashr_i32 s10, s12, 6
	s_ashr_i32 s41, s40, 31
	s_bfe_i64 s[14:15], s[4:5], 0x100000
	v_and_or_b32 v3, v1, s3, v3
	s_lshl_b32 s3, s10, 10
	s_lshl_b64 s[6:7], s[40:41], 19
	s_lshl_b64 s[14:15], s[14:15], 19
	s_add_u32 s44, s76, s14
	v_lshlrev_b32_e32 v4, 5, v12
	v_bfe_i32 v14, v0, 0, 16
	v_lshlrev_b32_e32 v0, 1, v1
	v_lshrrev_b32_e32 v2, 2, v1
	s_addc_u32 s45, s77, s15
	s_add_i32 s28, s3, 0
	v_and_b32_e32 v4, 32, v4
	v_and_b32_e32 v0, 24, v0
	v_and_b32_e32 v2, 4, v2
	s_add_i32 m0, s28, 0x10000
	v_or3_b32 v0, v3, v2, v0
	v_add_lshl_u32 v2, v4, v14, 1
	global_load_lds_dwordx4 v130, s[44:45]
	s_add_i32 m0, s28, 0x12000
	v_lshl_add_u32 v134, v0, 11, v2
	s_add_u32 s14, s44, 0x40000
	global_load_lds_dwordx4 v134, s[44:45]
	s_addc_u32 s15, s45, 0
	s_add_i32 m0, s28, 0x14000
	v_lshl_add_u32 v132, v1, 11, v2
	global_load_lds_dwordx4 v130, s[14:15]
	s_add_i32 m0, s28, 0x16000
	s_add_u32 s42, s8, s6
	s_addc_u32 s43, s9, s7
	s_add_i32 s29, s28, 0x2000
	global_load_lds_dwordx4 v134, s[14:15]
	s_mov_b32 m0, s28
	s_add_u32 s6, s42, 0x40000
	global_load_lds_dwordx4 v128, s[42:43]
	s_mov_b32 m0, s29
	s_addc_u32 s7, s43, 0
	s_add_i32 s30, s28, 0x4000
	global_load_lds_dwordx4 v132, s[42:43]
	s_mov_b32 m0, s30
	s_add_i32 s31, s28, 0x6000
	global_load_lds_dwordx4 v128, s[6:7]
	s_mov_b32 m0, s31
	v_mov_b32_e32 v131, 0
	global_load_lds_dwordx4 v132, s[6:7]
	v_mov_b32_e32 v135, v131
	v_mov_b32_e32 v129, v131
	v_mov_b32_e32 v133, v131
	s_cmp_eq_u32 s5, 1
	s_mov_b32 s33, 0
	v_lshl_add_u64 v[6:7], s[44:45], 0, v[130:131]
	v_lshl_add_u64 v[4:5], s[44:45], 0, v[134:135]
	v_lshl_add_u64 v[0:1], s[42:43], 0, v[128:129]
	s_cselect_b64 s[6:7], -1, 0
	s_cmp_lg_u32 s5, 1
	v_lshl_add_u64 v[2:3], s[42:43], 0, v[132:133]
	s_cbranch_scc1 .LBB0_727
	s_barrier

; #define PG8_STAGE(bufoff, gbase, voff) do { _Pragma("unroll") for (int _i = 0; _i < 2; ++_i) \
;         __builtin_amdgcn_global_load_lds((const unsigned*)((const char*)(gbase) + (voff)[_i]), (PG8_LAS unsigned*)(lds + (bufoff) + ldsw + _i * 8192), 16, 0, 0); } while (0)
; #define PG8_LDA(dst, b, h) do { _Pragma("unroll") for (int m = 0; m < 4; ++m) _Pragma("unroll") for (int k = 0; k < 2; ++k) dst[m][k] = *(const PG8_LAS bf16x8*)(lds + PG8_SA(b, h) + aoff + m * 2048 + k * 1024); } while (0)
; #define PG8_LDB(dst, b, h) do { _Pragma("unroll") for (int n = 0; n < 2; ++n) _Pragma("unroll") for (int k = 0; k < 2; ++k) dst[n][k] = *(const PG8_LAS bf16x8*)(lds + PG8_SB(b, h) + boff + n * 2048 + k * 1024); } while (0)
; #define PG8_MMA(ai, bj, At, Bt) do { __builtin_amdgcn_s_setprio(1); _Pragma("unroll") for (int m = 0; m < 4; ++m) _Pragma("unroll") for (int n = 0; n < 2; ++n) _Pragma("unroll") for (int k = 0; k < 2; ++k) \
;         acc[ai][bj][m][n] = __builtin_amdgcn_mfma_f32_16x16x32_bf16(Bt[n][k], At[m][k], acc[ai][bj][m][n], 0, 0, 0); __builtin_amdgcn_s_setprio(0); } while (0)
; #define PG8_WAIT_V(n) asm volatile("s_waitcnt vmcnt(" #n ")" ::: "memory")
; #define PG8_WAIT_L(n) asm volatile("s_waitcnt lgkmcnt(" #n ")" ::: "memory")
; #define PG8_BAR __builtin_amdgcn_s_barrier()
; #define PG8_SCHED __builtin_amdgcn_sched_barrier(0)
; template <class Epi, class Sched, bool ALIGN_EPI = false, bool SP2 = false>
; __device__ __forceinline__ void gemm_phase(PG8_LAS unsigned char* lds, const Gemm g, const Sched& S, const Epi& E) {
;     ...
;             if constexpr (SP2) {
;             PG8_LDB(B0, 0, 0); PG8_LDB(B1, 0, 1); PG8_SCHED; PG8_LDA(At, 0, 0); PG8_STAGE(PG8_SA(1, 1), a1 + hstep, voffA);
;             PG8_WAIT_V(8); PG8_WAIT_L(0); PG8_BAR; PG8_MMA(0, 0, At, B0); PG8_MMA(0, 1, At, B1); PG8_BAR; PG8_SCHED;
.LBB0_737:
	ds_read_b128 v[144:147], v155
	ds_read_b128 v[148:151], v155 offset:1024
	ds_read_b128 v[160:163], v155 offset:2048
	ds_read_b128 v[164:167], v155 offset:3072
	ds_read_b128 v[168:171], v156
	ds_read_b128 v[172:175], v156 offset:1024
	ds_read_b128 v[176:179], v156 offset:2048
	ds_read_b128 v[180:183], v156 offset:3072
	s_add_u32 s44, s42, 0xfffc0080
	s_addc_u32 s45, s43, -1
	s_cmp_eq_u32 s60, 12
	s_cselect_b32 s47, s25, s45
	s_cselect_b32 s46, s56, s44
	s_cselect_b32 s45, s23, s59
	s_cselect_b32 s44, s57, s58
	v_lshl_add_u64 v[218:219], s[42:43], 0, v[136:137]
	s_add_i32 m0, s28, 0xc000
	ds_read_b128 v[184:187], v157
	ds_read_b128 v[188:191], v157 offset:1024
	ds_read_b128 v[192:195], v157 offset:2048
	ds_read_b128 v[196:199], v157 offset:3072
	ds_read_b128 v[200:203], v157 offset:4096
	ds_read_b128 v[206:209], v157 offset:5120
	ds_read_b128 v[210:213], v157 offset:6144
	ds_read_b128 v[214:217], v157 offset:7168
	s_cmp_lg_u32 s98, 0
	s_cbranch_scc1 .Lgr_p5_alt1
	global_load_lds_dwordx4 v[218:219], off
	v_lshl_add_u64 v[218:219], s[42:43], 0, v[138:139]
	s_add_i32 m0, s28, 0xe000
	s_nop 0
	global_load_lds_dwordx4 v[218:219], off
	s_waitcnt vmcnt(8)
	s_branch .Lgr_p5_join1

; #define PG8_STAGE(bufoff, gbase, voff) do { _Pragma("unroll") for (int _i = 0; _i < 2; ++_i) \
;         __builtin_amdgcn_global_load_lds((const unsigned*)((const char*)(gbase) + (voff)[_i]), (PG8_LAS unsigned*)(lds + (bufoff) + ldsw + _i * 8192), 16, 0, 0); } while (0)
; #define PG8_LDA(dst, b, h) do { _Pragma("unroll") for (int m = 0; m < 4; ++m) _Pragma("unroll") for (int k = 0; k < 2; ++k) dst[m][k] = *(const PG8_LAS bf16x8*)(lds + PG8_SA(b, h) + aoff + m * 2048 + k * 1024); } while (0)
; #define PG8_MMA(ai, bj, At, Bt) do { __builtin_amdgcn_s_setprio(1); _Pragma("unroll") for (int m = 0; m < 4; ++m) _Pragma("unroll") for (int n = 0; n < 2; ++n) _Pragma("unroll") for (int k = 0; k < 2; ++k) \
;         acc[ai][bj][m][n] = __builtin_amdgcn_mfma_f32_16x16x32_bf16(Bt[n][k], At[m][k], acc[ai][bj][m][n], 0, 0, 0); __builtin_amdgcn_s_setprio(0); } while (0)
; #define PG8_WAIT_V(n) asm volatile("s_waitcnt vmcnt(" #n ")" ::: "memory")
; #define PG8_WAIT_L(n) asm volatile("s_waitcnt lgkmcnt(" #n ")" ::: "memory")
; #define PG8_BAR __builtin_amdgcn_s_barrier()
; #define PG8_SCHED __builtin_amdgcn_sched_barrier(0)
; template <class Epi, class Sched, bool ALIGN_EPI = false, bool SP2 = false>
; __device__ __forceinline__ void gemm_phase(PG8_LAS unsigned char* lds, const Gemm g, const Sched& S, const Epi& E) {
;     ...
;             PG8_WAIT_V(8); PG8_WAIT_L(0); PG8_BAR; PG8_MMA(0, 0, At, B0); PG8_MMA(0, 1, At, B1); PG8_BAR; PG8_SCHED;
;             PG8_LDA(At, 0, 1); PG8_STAGE(PG8_SB(0, 0), b2, voffB); PG8_STAGE(PG8_SB(0, 1), b2 + hstep, voffB); PG8_STAGE(PG8_SA(0, 0), a2, voffA);
;             PG8_WAIT_V(8); PG8_WAIT_L(0); PG8_BAR; PG8_MMA(1, 0, At, B0); PG8_MMA(1, 1, At, B1); PG8_BAR; PG8_SCHED;
.Lgr_p5_join1:
	s_waitcnt lgkmcnt(0)
	s_barrier
	s_setprio 1
	s_waitcnt lgkmcnt(0)
	v_mfma_f32_16x16x32_bf16 v[124:127], v[144:147], v[184:187], v[124:127]
	v_mfma_f32_16x16x32_bf16 v[120:123], v[160:163], v[184:187], v[120:123]
	v_mfma_f32_16x16x32_bf16 v[108:111], v[144:147], v[192:195], v[108:111]
	v_mfma_f32_16x16x32_bf16 v[104:107], v[160:163], v[192:195], v[104:107]
	v_mfma_f32_16x16x32_bf16 v[92:95], v[144:147], v[200:203], v[92:95]
	v_mfma_f32_16x16x32_bf16 v[88:91], v[160:163], v[200:203], v[88:91]
	v_mfma_f32_16x16x32_bf16 v[76:79], v[144:147], v[210:213], v[76:79]
	v_mfma_f32_16x16x32_bf16 v[72:75], v[160:163], v[210:213], v[72:75]
	v_mfma_f32_16x16x32_bf16 v[124:127], v[148:151], v[188:191], v[124:127]
	v_mfma_f32_16x16x32_bf16 v[120:123], v[164:167], v[188:191], v[120:123]
	v_mfma_f32_16x16x32_bf16 v[108:111], v[148:151], v[196:199], v[108:111]
	v_mfma_f32_16x16x32_bf16 v[104:107], v[164:167], v[196:199], v[104:107]
	v_mfma_f32_16x16x32_bf16 v[92:95], v[148:151], v[206:209], v[92:95]
	v_mfma_f32_16x16x32_bf16 v[88:91], v[164:167], v[206:209], v[88:91]
	v_mfma_f32_16x16x32_bf16 v[76:79], v[148:151], v[214:217], v[76:79]
	v_mfma_f32_16x16x32_bf16 v[72:75], v[164:167], v[214:217], v[72:75]
	v_mfma_f32_16x16x32_bf16 v[116:119], v[168:171], v[184:187], v[116:119]
	v_mfma_f32_16x16x32_bf16 v[112:115], v[176:179], v[184:187], v[112:115]
	v_mfma_f32_16x16x32_bf16 v[100:103], v[168:171], v[192:195], v[100:103]
	v_mfma_f32_16x16x32_bf16 v[96:99], v[176:179], v[192:195], v[96:99]
	v_mfma_f32_16x16x32_bf16 v[84:87], v[168:171], v[200:203], v[84:87]
	v_mfma_f32_16x16x32_bf16 v[80:83], v[176:179], v[200:203], v[80:83]
	v_mfma_f32_16x16x32_bf16 v[68:71], v[168:171], v[210:213], v[68:71]
	v_mfma_f32_16x16x32_bf16 v[64:67], v[176:179], v[210:213], v[64:67]
	v_mfma_f32_16x16x32_bf16 v[116:119], v[172:175], v[188:191], v[116:119]
	v_mfma_f32_16x16x32_bf16 v[112:115], v[180:183], v[188:191], v[112:115]
	v_mfma_f32_16x16x32_bf16 v[100:103], v[172:175], v[196:199], v[100:103]
	v_mfma_f32_16x16x32_bf16 v[96:99], v[180:183], v[196:199], v[96:99]
	v_mfma_f32_16x16x32_bf16 v[84:87], v[172:175], v[206:209], v[84:87]
	v_mfma_f32_16x16x32_bf16 v[80:83], v[180:183], v[206:209], v[80:83]
	v_mfma_f32_16x16x32_bf16 v[68:71], v[172:175], v[214:217], v[68:71]
	v_mfma_f32_16x16x32_bf16 v[64:67], v[180:183], v[214:217], v[64:67]
	s_setprio 0
	s_barrier
	s_add_i32 s61, s41, s3
	v_lshl_add_u64 v[218:219], s[44:45], 0, v[130:131]
	s_mov_b32 m0, s61
	ds_read_b128 v[184:187], v157 offset:16384
	ds_read_b128 v[188:191], v157 offset:17408
	ds_read_b128 v[192:195], v157 offset:18432
	ds_read_b128 v[196:199], v157 offset:19456
	ds_read_b128 v[200:203], v157 offset:20480
	ds_read_b128 v[206:209], v157 offset:21504
	ds_read_b128 v[210:213], v157 offset:22528
	ds_read_b128 v[214:217], v157 offset:23552
	global_load_lds_dwordx4 v[218:219], off
	s_add_i32 m0, s61, 0x2000
	s_add_u32 s62, s44, 0x40000
	v_lshl_add_u64 v[220:221], s[44:45], 0, v[134:135]
	s_addc_u32 s63, s45, 0
	s_add_i32 s61, s48, s3
	global_load_lds_dwordx4 v[220:221], off
	v_lshl_add_u64 v[222:223], s[62:63], 0, v[130:131]
	s_mov_b32 m0, s61
	v_lshl_add_u64 v[224:225], s[46:47], 0, v[132:133]
	global_load_lds_dwordx4 v[222:223], off
	v_lshl_add_u64 v[222:223], s[62:63], 0, v[134:135]
	s_add_i32 m0, s61, 0x2000
	s_nop 0
	global_load_lds_dwordx4 v[222:223], off
	v_lshl_add_u64 v[222:223], s[46:47], 0, v[128:129]
	s_mov_b32 m0, s28
	s_nop 0
	global_load_lds_dwordx4 v[222:223], off
	s_mov_b32 m0, s29
	s_nop 0
	global_load_lds_dwordx4 v[224:225], off
	s_waitcnt vmcnt(24)
	s_cmp_lg_u32 s98, 0
	s_cbranch_scc1 .Lgr_p5_skip2
	s_waitcnt vmcnt(8)
.Lgr_p5_skip2:
	s_waitcnt lgkmcnt(0)
	s_barrier
	s_setprio 1
	s_waitcnt lgkmcnt(0)
	v_mfma_f32_16x16x32_bf16 v[60:63], v[144:147], v[184:187], v[60:63]
	v_mfma_f32_16x16x32_bf16 v[56:59], v[160:163], v[184:187], v[56:59]
	v_mfma_f32_16x16x32_bf16 v[44:47], v[144:147], v[192:195], v[44:47]
	v_mfma_f32_16x16x32_bf16 v[40:43], v[160:163], v[192:195], v[40:43]
	v_mfma_f32_16x16x32_bf16 v[28:31], v[144:147], v[200:203], v[28:31]
	v_mfma_f32_16x16x32_bf16 v[24:27], v[160:163], v[200:203], v[24:27]
	v_mfma_f32_16x16x32_bf16 v[12:15], v[144:147], v[210:213], v[12:15]
	v_mfma_f32_16x16x32_bf16 v[8:11], v[160:163], v[210:213], v[8:11]
	v_mfma_f32_16x16x32_bf16 v[60:63], v[148:151], v[188:191], v[60:63]
	v_mfma_f32_16x16x32_bf16 v[56:59], v[164:167], v[188:191], v[56:59]
	v_mfma_f32_16x16x32_bf16 v[44:47], v[148:151], v[196:199], v[44:47]
	v_mfma_f32_16x16x32_bf16 v[40:43], v[164:167], v[196:199], v[40:43]
	v_mfma_f32_16x16x32_bf16 v[28:31], v[148:151], v[206:209], v[28:31]
	v_mfma_f32_16x16x32_bf16 v[24:27], v[164:167], v[206:209], v[24:27]
	v_mfma_f32_16x16x32_bf16 v[12:15], v[148:151], v[214:217], v[12:15]
	v_mfma_f32_16x16x32_bf16 v[8:11], v[164:167], v[214:217], v[8:11]
	v_mfma_f32_16x16x32_bf16 v[52:55], v[168:171], v[184:187], v[52:55]
	v_mfma_f32_16x16x32_bf16 v[48:51], v[176:179], v[184:187], v[48:51]
	v_mfma_f32_16x16x32_bf16 v[36:39], v[168:171], v[192:195], v[36:39]
	v_mfma_f32_16x16x32_bf16 v[32:35], v[176:179], v[192:195], v[32:35]
	v_mfma_f32_16x16x32_bf16 v[20:23], v[168:171], v[200:203], v[20:23]
	v_mfma_f32_16x16x32_bf16 v[16:19], v[176:179], v[200:203], v[16:19]
	v_mfma_f32_16x16x32_bf16 v[4:7], v[168:171], v[210:213], v[4:7]
	v_mfma_f32_16x16x32_bf16 v[0:3], v[176:179], v[210:213], v[0:3]
	v_mfma_f32_16x16x32_bf16 v[52:55], v[172:175], v[188:191], v[52:55]
	v_mfma_f32_16x16x32_bf16 v[48:51], v[180:183], v[188:191], v[48:51]
	v_mfma_f32_16x16x32_bf16 v[36:39], v[172:175], v[196:199], v[36:39]
	v_mfma_f32_16x16x32_bf16 v[32:35], v[180:183], v[196:199], v[32:35]
	v_mfma_f32_16x16x32_bf16 v[20:23], v[172:175], v[206:209], v[20:23]
	v_mfma_f32_16x16x32_bf16 v[16:19], v[180:183], v[206:209], v[16:19]
	v_mfma_f32_16x16x32_bf16 v[4:7], v[172:175], v[214:217], v[4:7]
	v_mfma_f32_16x16x32_bf16 v[0:3], v[180:183], v[214:217], v[0:3]
	s_setprio 0
	s_barrier
; #define PG8_STAGE(bufoff, gbase, voff) do { _Pragma("unroll") for (int _i = 0; _i < 2; ++_i) \
;         __builtin_amdgcn_global_load_lds((const unsigned*)((const char*)(gbase) + (voff)[_i]), (PG8_LAS unsigned*)(lds + (bufoff) + ldsw + _i * 8192), 16, 0, 0); } while (0)
; #define PG8_LDA(dst, b, h) do { _Pragma("unroll") for (int m = 0; m < 4; ++m) _Pragma("unroll") for (int k = 0; k < 2; ++k) dst[m][k] = *(const PG8_LAS bf16x8*)(lds + PG8_SA(b, h) + aoff + m * 2048 + k * 1024); } while (0)
; #define PG8_LDB(dst, b, h) do { _Pragma("unroll") for (int n = 0; n < 2; ++n) _Pragma("unroll") for (int k = 0; k < 2; ++k) dst[n][k] = *(const PG8_LAS bf16x8*)(lds + PG8_SB(b, h) + boff + n * 2048 + k * 1024); } while (0)
; #define PG8_MMA(ai, bj, At, Bt) do { __builtin_amdgcn_s_setprio(1); _Pragma("unroll") for (int m = 0; m < 4; ++m) _Pragma("unroll") for (int n = 0; n < 2; ++n) _Pragma("unroll") for (int k = 0; k < 2; ++k) \
;         acc[ai][bj][m][n] = __builtin_amdgcn_mfma_f32_16x16x32_bf16(Bt[n][k], At[m][k], acc[ai][bj][m][n], 0, 0, 0); __builtin_amdgcn_s_setprio(0); } while (0)
; #define PG8_WAIT_V(n) asm volatile("s_waitcnt vmcnt(" #n ")" ::: "memory")
; #define PG8_WAIT_L(n) asm volatile("s_waitcnt lgkmcnt(" #n ")" ::: "memory")
; #define PG8_BAR __builtin_amdgcn_s_barrier()
; #define PG8_SCHED __builtin_amdgcn_sched_barrier(0)
; template <class Epi, class Sched, bool ALIGN_EPI = false, bool SP2 = false>
; __device__ __forceinline__ void gemm_phase(PG8_LAS unsigned char* lds, const Gemm g, const Sched& S, const Epi& E) {
;     ...
;             PG8_LDB(B0, 1, 0); PG8_LDB(B1, 1, 1); PG8_SCHED; PG8_LDA(At, 1, 0); PG8_STAGE(PG8_SA(0, 1), a2 + hstep, voffA);
;             PG8_WAIT_V(8); PG8_WAIT_L(0); PG8_BAR; PG8_MMA(0, 0, At, B0); PG8_MMA(0, 1, At, B1); PG8_BAR; PG8_SCHED;
;             PG8_LDA(At, 1, 1); PG8_STAGE(PG8_SB(1, 0), b3, voffB); PG8_STAGE(PG8_SB(1, 1), b3 + hstep, voffB); PG8_STAGE(PG8_SA(1, 0), a3, voffA);
;             PG8_WAIT_V(8); PG8_WAIT_L(0); PG8_BAR; PG8_MMA(1, 0, At, B0); PG8_MMA(1, 1, At, B1); PG8_BAR; PG8_SCHED;
	s_add_i32 s61, 0, 0x18000
	v_add_u32_e32 v159, s61, v153
	s_add_i32 s62, 0, 0x1c000
	ds_read_b128 v[144:147], v159
	ds_read_b128 v[148:151], v159 offset:1024
	ds_read_b128 v[160:163], v159 offset:2048
	ds_read_b128 v[164:167], v159 offset:3072
	v_add_u32_e32 v159, s62, v153
	ds_read_b128 v[168:171], v159
	ds_read_b128 v[172:175], v159 offset:1024
	ds_read_b128 v[176:179], v159 offset:2048
	ds_read_b128 v[180:183], v159 offset:3072
	s_add_u32 s46, s46, 0x40000
	s_addc_u32 s47, s47, 0
	s_mov_b32 m0, s30
	v_lshl_add_u64 v[226:227], s[46:47], 0, v[128:129]
	ds_read_b128 v[184:187], v157 offset:32768
	ds_read_b128 v[188:191], v157 offset:33792
	ds_read_b128 v[192:195], v157 offset:34816
	ds_read_b128 v[196:199], v157 offset:35840
	ds_read_b128 v[200:203], v157 offset:36864
	ds_read_b128 v[206:209], v157 offset:37888
	ds_read_b128 v[210:213], v157 offset:38912
	ds_read_b128 v[214:217], v157 offset:39936
	global_load_lds_dwordx4 v[226:227], off
	v_lshl_add_u64 v[226:227], s[46:47], 0, v[132:133]
	s_mov_b32 m0, s31
	s_nop 0
	global_load_lds_dwordx4 v[226:227], off
	s_waitcnt vmcnt(24)
	s_cmp_lg_u32 s98, 0
	s_cbranch_scc1 .Lgr_p5_skip3
	s_waitcnt vmcnt(8)
.Lgr_p5_skip3:
	s_waitcnt lgkmcnt(0)
	s_barrier
	s_setprio 1
	s_waitcnt lgkmcnt(0)
	v_mfma_f32_16x16x32_bf16 v[124:127], v[144:147], v[184:187], v[124:127]
	v_mfma_f32_16x16x32_bf16 v[120:123], v[160:163], v[184:187], v[120:123]
	v_mfma_f32_16x16x32_bf16 v[108:111], v[144:147], v[192:195], v[108:111]
	v_mfma_f32_16x16x32_bf16 v[104:107], v[160:163], v[192:195], v[104:107]
	v_mfma_f32_16x16x32_bf16 v[92:95], v[144:147], v[200:203], v[92:95]
	v_mfma_f32_16x16x32_bf16 v[88:91], v[160:163], v[200:203], v[88:91]
	v_mfma_f32_16x16x32_bf16 v[76:79], v[144:147], v[210:213], v[76:79]
	v_mfma_f32_16x16x32_bf16 v[72:75], v[160:163], v[210:213], v[72:75]
	v_mfma_f32_16x16x32_bf16 v[124:127], v[148:151], v[188:191], v[124:127]
	v_mfma_f32_16x16x32_bf16 v[120:123], v[164:167], v[188:191], v[120:123]
	v_mfma_f32_16x16x32_bf16 v[108:111], v[148:151], v[196:199], v[108:111]
	v_mfma_f32_16x16x32_bf16 v[104:107], v[164:167], v[196:199], v[104:107]
	v_mfma_f32_16x16x32_bf16 v[92:95], v[148:151], v[206:209], v[92:95]
	v_mfma_f32_16x16x32_bf16 v[88:91], v[164:167], v[206:209], v[88:91]
	v_mfma_f32_16x16x32_bf16 v[76:79], v[148:151], v[214:217], v[76:79]
	v_mfma_f32_16x16x32_bf16 v[72:75], v[164:167], v[214:217], v[72:75]
	v_mfma_f32_16x16x32_bf16 v[116:119], v[168:171], v[184:187], v[116:119]
	v_mfma_f32_16x16x32_bf16 v[112:115], v[176:179], v[184:187], v[112:115]
	v_mfma_f32_16x16x32_bf16 v[100:103], v[168:171], v[192:195], v[100:103]
	v_mfma_f32_16x16x32_bf16 v[96:99], v[176:179], v[192:195], v[96:99]
	v_mfma_f32_16x16x32_bf16 v[84:87], v[168:171], v[200:203], v[84:87]
	v_mfma_f32_16x16x32_bf16 v[80:83], v[176:179], v[200:203], v[80:83]
	v_mfma_f32_16x16x32_bf16 v[68:71], v[168:171], v[210:213], v[68:71]
	v_mfma_f32_16x16x32_bf16 v[64:67], v[176:179], v[210:213], v[64:67]
	v_mfma_f32_16x16x32_bf16 v[116:119], v[172:175], v[188:191], v[116:119]
	v_mfma_f32_16x16x32_bf16 v[112:115], v[180:183], v[188:191], v[112:115]
	v_mfma_f32_16x16x32_bf16 v[100:103], v[172:175], v[196:199], v[100:103]
	v_mfma_f32_16x16x32_bf16 v[96:99], v[180:183], v[196:199], v[96:99]
	v_mfma_f32_16x16x32_bf16 v[84:87], v[172:175], v[206:209], v[84:87]
	v_mfma_f32_16x16x32_bf16 v[80:83], v[180:183], v[206:209], v[80:83]
	v_mfma_f32_16x16x32_bf16 v[68:71], v[172:175], v[214:217], v[68:71]
	v_mfma_f32_16x16x32_bf16 v[64:67], v[180:183], v[214:217], v[64:67]
	s_setprio 0
	s_barrier
	s_add_i32 s46, s61, s3
	v_lshl_add_u64 v[218:219], v[218:219], 0, s[10:11]
	s_mov_b32 m0, s46
	ds_read_b128 v[184:187], v157 offset:49152
	ds_read_b128 v[188:191], v157 offset:50176
	ds_read_b128 v[192:195], v157 offset:51200
	ds_read_b128 v[196:199], v157 offset:52224
	ds_read_b128 v[200:203], v157 offset:53248
	ds_read_b128 v[206:209], v157 offset:54272
	ds_read_b128 v[210:213], v157 offset:55296
	ds_read_b128 v[214:217], v157 offset:56320
	global_load_lds_dwordx4 v[218:219], off
	s_add_i32 m0, s46, 0x2000
	s_add_u32 s44, s44, 0x40080
	v_lshl_add_u64 v[218:219], v[220:221], 0, s[10:11]
	s_addc_u32 s45, s45, 0
	s_add_i32 s46, s62, s3
	global_load_lds_dwordx4 v[218:219], off
	v_lshl_add_u64 v[218:219], s[44:45], 0, v[130:131]
	s_mov_b32 m0, s46
	s_nop 0
	global_load_lds_dwordx4 v[218:219], off
	v_lshl_add_u64 v[218:219], s[44:45], 0, v[134:135]
	s_add_i32 m0, s46, 0x2000
	s_nop 0
	global_load_lds_dwordx4 v[218:219], off
	v_lshl_add_u64 v[218:219], v[222:223], 0, s[10:11]
	s_mov_b32 m0, s34
	s_nop 0
	global_load_lds_dwordx4 v[218:219], off
	v_lshl_add_u64 v[218:219], v[224:225], 0, s[10:11]
	s_mov_b32 m0, s35
	s_nop 0
	global_load_lds_dwordx4 v[218:219], off
	s_waitcnt vmcnt(8)
	s_waitcnt lgkmcnt(0)
	s_barrier
;     __device__ __forceinline__ void operator()(const f32x4 (&acc)[2][2][4][2], const Unit& u, int wr, int wc, int fr, int fq) const {
;         const int row0 = u.pm * BM + wr * 64 + fr, col0 = u.pn * BM + wc * 32 + 8 * fq;
; #pragma unroll
;         for (int ai = 0; ai < 2; ++ai)
; #pragma unroll
;             for (int m = 0; m < 4; ++m) { const int row = row0 + ai * HALF + m * 16; const float rs = __builtin_amdgcn_rsqf(ssq[row] * (1.0f / 1024.0f) + 1e-6f); bf16_t* rowp = U + (size_t)row * 4096 + col0;
; #pragma unroll
;                 for (int bj = 0; bj < 2; ++bj) { const f32x4 v0 = acc[ai][bj][m][0], v1 = acc[ai][bj][m][1];
;                     float f[8] = {v0[0], v0[1], v0[2], v0[3], v1[0], v1[1], v1[2], v1[3]};
; #pragma unroll
;                     for (int e = 0; e < 8; ++e) { const float r = fmaxf(f[e] * rs, 0.f); f[e] = r * r; }
;                     *(u32x4*)(rowp + bj * HALF) = pack8(f); } }
; template <class Epi, class Sched, bool ALIGN_EPI = false, bool SP2 = false>
; __device__ __forceinline__ void gemm_phase(PG8_LAS unsigned char* lds, const Gemm g, const Sched& S, const Epi& E) {
;     ...
;             PG8_WAIT_V(8); PG8_WAIT_L(0); PG8_BAR; PG8_MMA(1, 0, At, B0); PG8_MMA(1, 1, At, B1); PG8_BAR; PG8_SCHED;
;             } else {
;             PG8_LDB(B0, 0, 0); PG8_SCHED; PG8_LDA(At, 0, 0); PG8_STAGE(PG8_SA(1, 1), a1 + hstep, voffA);
;             PG8_WAIT_L(8); PG8_BAR; PG8_WAIT_L(0); PG8_MMA(0, 0, At, B0); PG8_BAR; PG8_SCHED;
;             PG8_LDB(B1, 0, 1); PG8_STAGE(PG8_SB(0, 0), b2, voffB);
;             PG8_BAR; PG8_WAIT_L(0); PG8_MMA(0, 1, At, B1); PG8_BAR;
;             PG8_LDA(At, 0, 1); PG8_STAGE(PG8_SA(0, 0), a2, voffA);
;             PG8_BAR; PG8_WAIT_L(0); PG8_MMA(1, 0, At, B0); PG8_BAR; PG8_SCHED;
;             PG8_STAGE(PG8_SB(0, 1), b2 + hstep, voffB);
;             PG8_WAIT_V(6); PG8_BAR; PG8_MMA(1, 1, At, B1); PG8_BAR;
;             PG8_LDB(B0, 1, 0); PG8_SCHED; PG8_LDA(At, 1, 0); PG8_STAGE(PG8_SA(0, 1), a2 + hstep, voffA);
;             PG8_WAIT_L(8); PG8_BAR; PG8_WAIT_L(0); PG8_MMA(0, 0, At, B0); PG8_BAR; PG8_SCHED;
;             PG8_LDB(B1, 1, 1); PG8_STAGE(PG8_SB(1, 0), b3, voffB);
;             PG8_BAR; PG8_WAIT_L(0); PG8_MMA(0, 1, At, B1); PG8_BAR;
;             PG8_LDA(At, 1, 1); PG8_STAGE(PG8_SA(1, 0), a3, voffA);
;             PG8_BAR; PG8_WAIT_L(0); PG8_MMA(1, 0, At, B0); PG8_BAR; PG8_SCHED;
	s_setprio 1
	s_waitcnt lgkmcnt(0)
	v_mfma_f32_16x16x32_bf16 v[60:63], v[144:147], v[184:187], v[60:63]
	v_mfma_f32_16x16x32_bf16 v[56:59], v[160:163], v[184:187], v[56:59]
	v_mfma_f32_16x16x32_bf16 v[44:47], v[144:147], v[192:195], v[44:47]
	v_mfma_f32_16x16x32_bf16 v[40:43], v[160:163], v[192:195], v[40:43]
	v_mfma_f32_16x16x32_bf16 v[28:31], v[144:147], v[200:203], v[28:31]
	v_mfma_f32_16x16x32_bf16 v[24:27], v[160:163], v[200:203], v[24:27]
	v_mfma_f32_16x16x32_bf16 v[12:15], v[144:147], v[210:213], v[12:15]
	v_mfma_f32_16x16x32_bf16 v[8:11], v[160:163], v[210:213], v[8:11]
	v_mfma_f32_16x16x32_bf16 v[60:63], v[148:151], v[188:191], v[60:63]
	v_mfma_f32_16x16x32_bf16 v[56:59], v[164:167], v[188:191], v[56:59]
	v_mfma_f32_16x16x32_bf16 v[44:47], v[148:151], v[196:199], v[44:47]
	v_mfma_f32_16x16x32_bf16 v[40:43], v[164:167], v[196:199], v[40:43]
	v_mfma_f32_16x16x32_bf16 v[28:31], v[148:151], v[206:209], v[28:31]
	v_mfma_f32_16x16x32_bf16 v[24:27], v[164:167], v[206:209], v[24:27]
	v_mfma_f32_16x16x32_bf16 v[12:15], v[148:151], v[214:217], v[12:15]
	v_mfma_f32_16x16x32_bf16 v[8:11], v[164:167], v[214:217], v[8:11]
	v_mfma_f32_16x16x32_bf16 v[52:55], v[168:171], v[184:187], v[52:55]
	v_mfma_f32_16x16x32_bf16 v[48:51], v[176:179], v[184:187], v[48:51]
	v_mfma_f32_16x16x32_bf16 v[36:39], v[168:171], v[192:195], v[36:39]
	v_mfma_f32_16x16x32_bf16 v[32:35], v[176:179], v[192:195], v[32:35]
	v_mfma_f32_16x16x32_bf16 v[20:23], v[168:171], v[200:203], v[20:23]
	v_mfma_f32_16x16x32_bf16 v[16:19], v[176:179], v[200:203], v[16:19]
	v_mfma_f32_16x16x32_bf16 v[4:7], v[168:171], v[210:213], v[4:7]
	v_mfma_f32_16x16x32_bf16 v[0:3], v[176:179], v[210:213], v[0:3]
	v_mfma_f32_16x16x32_bf16 v[52:55], v[172:175], v[188:191], v[52:55]
	v_mfma_f32_16x16x32_bf16 v[48:51], v[180:183], v[188:191], v[48:51]
	v_mfma_f32_16x16x32_bf16 v[36:39], v[172:175], v[196:199], v[36:39]
	v_mfma_f32_16x16x32_bf16 v[32:35], v[180:183], v[196:199], v[32:35]
	v_mfma_f32_16x16x32_bf16 v[20:23], v[172:175], v[206:209], v[20:23]
	v_mfma_f32_16x16x32_bf16 v[16:19], v[180:183], v[206:209], v[16:19]
	v_mfma_f32_16x16x32_bf16 v[4:7], v[172:175], v[214:217], v[4:7]
	v_mfma_f32_16x16x32_bf16 v[0:3], v[180:183], v[214:217], v[0:3]
	s_setprio 0
	s_barrier
	s_add_i32 s60, s60, 2
	s_add_u32 s42, s42, 0x100
	s_addc_u32 s43, s43, 0
	s_add_u32 s58, s58, 0x100
	s_addc_u32 s59, s59, 0
	s_mov_b32 s98, 0
	s_cmp_gt_u32 s60, 13
	s_cbranch_scc0 .LBB0_737
	s_and_b64 vcc, exec, s[12:13]
	s_cbranch_vccz .LBB0_740
	s_barrier
.LBB0_740:
	s_add_u32 s100, s56, 0x40080
	s_addc_u32 s101, s25, 0
	v_lshl_add_u64 v[218:219], s[100:101], 0, v[136:137]
	s_add_i32 m0, s28, 0xc000
	s_nop 0
	global_load_lds_dwordx4 v[218:219], off
	v_lshl_add_u64 v[218:219], s[100:101], 0, v[138:139]
	s_add_i32 m0, s28, 0xe000
	s_nop 0
	global_load_lds_dwordx4 v[218:219], off
	s_mov_b32 s98, 1
	v_lshl_add_u32 v148, s40, 8, v152
	v_lshlrev_b32_e32 v150, 2, v148
	global_load_dword v228, v150, s[68:69]
	global_load_dword v230, v150, s[68:69] offset:64
	global_load_dword v232, v150, s[68:69] offset:128
	global_load_dword v234, v150, s[68:69] offset:192
	global_load_dword v236, v150, s[68:69] offset:512
	global_load_dword v238, v150, s[68:69] offset:576
	global_load_dword v240, v150, s[68:69] offset:640
	global_load_dword v242, v150, s[68:69] offset:704
	v_bfe_u32 v144, v204, 2, 4
	v_and_or_b32 v149, v152, -16, v144
	v_and_b32_e32 v144, 3, v204
	v_lshlrev_b32_e32 v144, 3, v144
	v_and_b32_e32 v146, 0xffffffe7, v154
	v_or_b32_e32 v146, v146, v144
	v_lshl_add_u32 v149, s40, 8, v149
	v_lshl_or_b32 v146, s55, 8, v146
	v_lshlrev_b32_e32 v146, 1, v146
	v_lshl_add_u32 v151, v149, 13, v146
	v_lshrrev_b32_e32 v144, 6, v204
	v_mul_u32_u24_e32 v144, 0x500, v144
	v_add_u32_e32 v144, 0x20000, v144
	v_and_b32_e32 v244, 15, v204
	v_mul_u32_u24_e32 v244, 0x50, v244
	v_bfe_u32 v145, v204, 4, 2
	v_lshl_add_u32 v244, v145, 4, v244
	v_add_u32_e32 v244, v244, v144
	v_bfe_u32 v245, v204, 2, 4
	v_mul_u32_u24_e32 v245, 0x50, v245
	v_and_b32_e32 v145, 3, v204
	v_lshl_add_u32 v245, v145, 4, v245
	v_add_u32_e32 v245, v245, v144
	s_waitcnt vmcnt(0)
	v_fmamk_f32 v228, v228, 0x3a800000, v158
	v_fmamk_f32 v230, v230, 0x3a800000, v158
	v_fmamk_f32 v232, v232, 0x3a800000, v158
	v_fmamk_f32 v234, v234, 0x3a800000, v158
	v_fmamk_f32 v236, v236, 0x3a800000, v158
	v_fmamk_f32 v238, v238, 0x3a800000, v158
	v_fmamk_f32 v240, v240, 0x3a800000, v158
	v_fmamk_f32 v242, v242, 0x3a800000, v158
	v_rsq_f32_e32 v228, v228
	v_rsq_f32_e32 v230, v230
	v_rsq_f32_e32 v232, v232
	v_rsq_f32_e32 v234, v234
	v_rsq_f32_e32 v236, v236
	v_rsq_f32_e32 v238, v238
	v_rsq_f32_e32 v240, v240
	v_rsq_f32_e32 v242, v242
	s_nop 0
	v_pk_mul_f32 v[124:125], v[124:125], v[228:229] op_sel_hi:[1,0]
	v_pk_mul_f32 v[126:127], v[126:127], v[228:229] op_sel_hi:[1,0]
	v_pk_mul_f32 v[120:121], v[120:121], v[228:229] op_sel_hi:[1,0]
	v_pk_mul_f32 v[122:123], v[122:123], v[228:229] op_sel_hi:[1,0]
	v_max_f32_e32 v124, 0, v124
	v_max_f32_e32 v125, 0, v125
	v_max_f32_e32 v126, 0, v126
	v_max_f32_e32 v127, 0, v127
	v_max_f32_e32 v120, 0, v120
	v_max_f32_e32 v121, 0, v121
	v_max_f32_e32 v122, 0, v122
	v_max_f32_e32 v123, 0, v123
	v_pk_mul_f32 v[124:125], v[124:125], v[124:125]
	v_pk_mul_f32 v[126:127], v[126:127], v[126:127]
	v_pk_mul_f32 v[120:121], v[120:121], v[120:121]
	v_pk_mul_f32 v[122:123], v[122:123], v[122:123]
	v_cvt_pk_bf16_f32 v124, v124, v125
	v_cvt_pk_bf16_f32 v125, v126, v127
	v_cvt_pk_bf16_f32 v126, v120, v121
	v_cvt_pk_bf16_f32 v127, v122, v123
	ds_write_b128 v244, v[124:127]
	ds_read_b128 v[120:123], v245
	v_pk_mul_f32 v[116:117], v[116:117], v[228:229] op_sel_hi:[1,0]
; __device__ __forceinline__ u32x4 pack8(const float (&f)[8]) { u32x4 w; w.x = cvt_pk_bf16(f[0], f[1]); w.y = cvt_pk_bf16(f[2], f[3]); w.z = cvt_pk_bf16(f[4], f[5]); w.w = cvt_pk_bf16(f[6], f[7]); return w; }
;     __device__ __forceinline__ void operator()(const f32x4 (&acc)[2][2][4][2], const Unit& u, int wr, int wc, int fr, int fq) const {
;         const int row0 = u.pm * BM + wr * 64 + fr, col0 = u.pn * BM + wc * 32 + 8 * fq;
; #pragma unroll
;         for (int ai = 0; ai < 2; ++ai)
; #pragma unroll
;             for (int m = 0; m < 4; ++m) { const int row = row0 + ai * HALF + m * 16; const float rs = __builtin_amdgcn_rsqf(ssq[row] * (1.0f / 1024.0f) + 1e-6f); bf16_t* rowp = U + (size_t)row * 4096 + col0;
; #pragma unroll
;                 for (int bj = 0; bj < 2; ++bj) { const f32x4 v0 = acc[ai][bj][m][0], v1 = acc[ai][bj][m][1];
;                     float f[8] = {v0[0], v0[1], v0[2], v0[3], v1[0], v1[1], v1[2], v1[3]};
; #pragma unroll
;                     for (int e = 0; e < 8; ++e) { const float r = fmaxf(f[e] * rs, 0.f); f[e] = r * r; }
;                     *(u32x4*)(rowp + bj * HALF) = pack8(f); } }
	v_pk_mul_f32 v[118:119], v[118:119], v[228:229] op_sel_hi:[1,0]
	v_pk_mul_f32 v[112:113], v[112:113], v[228:229] op_sel_hi:[1,0]
	v_pk_mul_f32 v[114:115], v[114:115], v[228:229] op_sel_hi:[1,0]
	v_max_f32_e32 v116, 0, v116
	v_max_f32_e32 v117, 0, v117
	v_max_f32_e32 v118, 0, v118
	v_max_f32_e32 v119, 0, v119
	v_max_f32_e32 v112, 0, v112
	v_max_f32_e32 v113, 0, v113
	v_max_f32_e32 v114, 0, v114
	v_max_f32_e32 v115, 0, v115
	v_pk_mul_f32 v[116:117], v[116:117], v[116:117]
	v_pk_mul_f32 v[118:119], v[118:119], v[118:119]
	v_pk_mul_f32 v[112:113], v[112:113], v[112:113]
	v_pk_mul_f32 v[114:115], v[114:115], v[114:115]
	v_cvt_pk_bf16_f32 v116, v116, v117
	v_cvt_pk_bf16_f32 v117, v118, v119
	v_cvt_pk_bf16_f32 v118, v112, v113
	v_cvt_pk_bf16_f32 v119, v114, v115
	ds_write_b128 v244, v[116:119]
	ds_read_b128 v[112:115], v245
	v_pk_mul_f32 v[108:109], v[108:109], v[230:231] op_sel_hi:[1,0]
	v_pk_mul_f32 v[110:111], v[110:111], v[230:231] op_sel_hi:[1,0]
	v_pk_mul_f32 v[104:105], v[104:105], v[230:231] op_sel_hi:[1,0]
	v_pk_mul_f32 v[106:107], v[106:107], v[230:231] op_sel_hi:[1,0]
	v_max_f32_e32 v108, 0, v108
	v_max_f32_e32 v109, 0, v109
	v_max_f32_e32 v110, 0, v110
	v_max_f32_e32 v111, 0, v111
	v_max_f32_e32 v104, 0, v104
	v_max_f32_e32 v105, 0, v105
	v_max_f32_e32 v106, 0, v106
	v_max_f32_e32 v107, 0, v107
	v_pk_mul_f32 v[108:109], v[108:109], v[108:109]
	v_pk_mul_f32 v[110:111], v[110:111], v[110:111]
	v_pk_mul_f32 v[104:105], v[104:105], v[104:105]
	v_pk_mul_f32 v[106:107], v[106:107], v[106:107]
	v_cvt_pk_bf16_f32 v108, v108, v109
	v_cvt_pk_bf16_f32 v109, v110, v111
	v_cvt_pk_bf16_f32 v110, v104, v105
	v_cvt_pk_bf16_f32 v111, v106, v107
	ds_write_b128 v244, v[108:111]
	ds_read_b128 v[104:107], v245
	v_pk_mul_f32 v[100:101], v[100:101], v[230:231] op_sel_hi:[1,0]
	v_pk_mul_f32 v[102:103], v[102:103], v[230:231] op_sel_hi:[1,0]
	v_pk_mul_f32 v[96:97], v[96:97], v[230:231] op_sel_hi:[1,0]
	v_pk_mul_f32 v[98:99], v[98:99], v[230:231] op_sel_hi:[1,0]
	v_max_f32_e32 v100, 0, v100
	v_max_f32_e32 v101, 0, v101
	v_max_f32_e32 v102, 0, v102
	v_max_f32_e32 v103, 0, v103
	v_max_f32_e32 v96, 0, v96
	v_max_f32_e32 v97, 0, v97
	v_max_f32_e32 v98, 0, v98
	v_max_f32_e32 v99, 0, v99
	v_pk_mul_f32 v[100:101], v[100:101], v[100:101]
	v_pk_mul_f32 v[102:103], v[102:103], v[102:103]
	v_pk_mul_f32 v[96:97], v[96:97], v[96:97]
	v_pk_mul_f32 v[98:99], v[98:99], v[98:99]
	v_cvt_pk_bf16_f32 v100, v100, v101
	v_cvt_pk_bf16_f32 v101, v102, v103
	v_cvt_pk_bf16_f32 v102, v96, v97
	v_cvt_pk_bf16_f32 v103, v98, v99
	ds_write_b128 v244, v[100:103]
	ds_read_b128 v[96:99], v245
	s_waitcnt lgkmcnt(6)
	global_store_dwordx4 v151, v[120:123], s[36:37]
	s_waitcnt lgkmcnt(4)
	global_store_dwordx4 v151, v[112:115], s[36:37] offset:256
	v_add_u32_e32 v151, 0x20000, v151
	s_waitcnt lgkmcnt(2)
	global_store_dwordx4 v151, v[104:107], s[36:37]
	s_waitcnt lgkmcnt(0)
	global_store_dwordx4 v151, v[96:99], s[36:37] offset:256
	v_pk_mul_f32 v[92:93], v[92:93], v[232:233] op_sel_hi:[1,0]
	v_pk_mul_f32 v[94:95], v[94:95], v[232:233] op_sel_hi:[1,0]
	v_pk_mul_f32 v[88:89], v[88:89], v[232:233] op_sel_hi:[1,0]
	v_pk_mul_f32 v[90:91], v[90:91], v[232:233] op_sel_hi:[1,0]
	v_max_f32_e32 v92, 0, v92
	v_max_f32_e32 v93, 0, v93
	v_max_f32_e32 v94, 0, v94
	v_max_f32_e32 v95, 0, v95
	v_max_f32_e32 v88, 0, v88
	v_max_f32_e32 v89, 0, v89
	v_max_f32_e32 v90, 0, v90
	v_max_f32_e32 v91, 0, v91
	v_pk_mul_f32 v[92:93], v[92:93], v[92:93]
	v_pk_mul_f32 v[94:95], v[94:95], v[94:95]
	v_pk_mul_f32 v[88:89], v[88:89], v[88:89]
	v_pk_mul_f32 v[90:91], v[90:91], v[90:91]
	v_cvt_pk_bf16_f32 v92, v92, v93
	v_cvt_pk_bf16_f32 v93, v94, v95
	v_cvt_pk_bf16_f32 v94, v88, v89
	v_cvt_pk_bf16_f32 v95, v90, v91
	ds_write_b128 v244, v[92:95]
	ds_read_b128 v[88:91], v245
	v_pk_mul_f32 v[84:85], v[84:85], v[232:233] op_sel_hi:[1,0]
	v_pk_mul_f32 v[86:87], v[86:87], v[232:233] op_sel_hi:[1,0]
	v_pk_mul_f32 v[80:81], v[80:81], v[232:233] op_sel_hi:[1,0]
	v_pk_mul_f32 v[82:83], v[82:83], v[232:233] op_sel_hi:[1,0]
	v_max_f32_e32 v84, 0, v84
	v_max_f32_e32 v85, 0, v85
	v_max_f32_e32 v86, 0, v86
	v_max_f32_e32 v87, 0, v87
	v_max_f32_e32 v80, 0, v80
	v_max_f32_e32 v81, 0, v81
	v_max_f32_e32 v82, 0, v82
	v_max_f32_e32 v83, 0, v83
	v_pk_mul_f32 v[84:85], v[84:85], v[84:85]
	v_pk_mul_f32 v[86:87], v[86:87], v[86:87]
	v_pk_mul_f32 v[80:81], v[80:81], v[80:81]
	v_pk_mul_f32 v[82:83], v[82:83], v[82:83]
	v_cvt_pk_bf16_f32 v84, v84, v85
	v_cvt_pk_bf16_f32 v85, v86, v87
	v_cvt_pk_bf16_f32 v86, v80, v81
	v_cvt_pk_bf16_f32 v87, v82, v83
	ds_write_b128 v244, v[84:87]
	ds_read_b128 v[80:83], v245
	v_pk_mul_f32 v[76:77], v[76:77], v[234:235] op_sel_hi:[1,0]
	v_pk_mul_f32 v[78:79], v[78:79], v[234:235] op_sel_hi:[1,0]
	v_pk_mul_f32 v[72:73], v[72:73], v[234:235] op_sel_hi:[1,0]
	v_pk_mul_f32 v[74:75], v[74:75], v[234:235] op_sel_hi:[1,0]
	v_max_f32_e32 v76, 0, v76
	v_max_f32_e32 v77, 0, v77
	v_max_f32_e32 v78, 0, v78
	v_max_f32_e32 v79, 0, v79
	v_max_f32_e32 v72, 0, v72
	v_max_f32_e32 v73, 0, v73
	v_max_f32_e32 v74, 0, v74
	v_max_f32_e32 v75, 0, v75
	v_pk_mul_f32 v[76:77], v[76:77], v[76:77]
	v_pk_mul_f32 v[78:79], v[78:79], v[78:79]
	v_pk_mul_f32 v[72:73], v[72:73], v[72:73]
	v_pk_mul_f32 v[74:75], v[74:75], v[74:75]
	v_cvt_pk_bf16_f32 v76, v76, v77
	v_cvt_pk_bf16_f32 v77, v78, v79
	v_cvt_pk_bf16_f32 v78, v72, v73
	v_cvt_pk_bf16_f32 v79, v74, v75
	ds_write_b128 v244, v[76:79]
	ds_read_b128 v[72:75], v245
	v_pk_mul_f32 v[68:69], v[68:69], v[234:235] op_sel_hi:[1,0]
	v_pk_mul_f32 v[70:71], v[70:71], v[234:235] op_sel_hi:[1,0]
	v_pk_mul_f32 v[64:65], v[64:65], v[234:235] op_sel_hi:[1,0]
	v_pk_mul_f32 v[66:67], v[66:67], v[234:235] op_sel_hi:[1,0]
	v_max_f32_e32 v68, 0, v68
	v_max_f32_e32 v69, 0, v69
	v_max_f32_e32 v70, 0, v70
	v_max_f32_e32 v71, 0, v71
	v_max_f32_e32 v64, 0, v64
	v_max_f32_e32 v65, 0, v65
	v_max_f32_e32 v66, 0, v66
	v_max_f32_e32 v67, 0, v67
	v_pk_mul_f32 v[68:69], v[68:69], v[68:69]
	v_pk_mul_f32 v[70:71], v[70:71], v[70:71]
	v_pk_mul_f32 v[64:65], v[64:65], v[64:65]
	v_pk_mul_f32 v[66:67], v[66:67], v[66:67]
	v_cvt_pk_bf16_f32 v68, v68, v69
	v_cvt_pk_bf16_f32 v69, v70, v71
	v_cvt_pk_bf16_f32 v70, v64, v65
	v_cvt_pk_bf16_f32 v71, v66, v67
	ds_write_b128 v244, v[68:71]
	ds_read_b128 v[64:67], v245
	v_add_u32_e32 v151, 0x20000, v151
	s_waitcnt lgkmcnt(6)
; __device__ __forceinline__ u32x4 pack8(const float (&f)[8]) { u32x4 w; w.x = cvt_pk_bf16(f[0], f[1]); w.y = cvt_pk_bf16(f[2], f[3]); w.z = cvt_pk_bf16(f[4], f[5]); w.w = cvt_pk_bf16(f[6], f[7]); return w; }
;     __device__ __forceinline__ void operator()(const f32x4 (&acc)[2][2][4][2], const Unit& u, int wr, int wc, int fr, int fq) const {
;         const int row0 = u.pm * BM + wr * 64 + fr, col0 = u.pn * BM + wc * 32 + 8 * fq;
; #pragma unroll
;         for (int ai = 0; ai < 2; ++ai)
; #pragma unroll
;             for (int m = 0; m < 4; ++m) { const int row = row0 + ai * HALF + m * 16; const float rs = __builtin_amdgcn_rsqf(ssq[row] * (1.0f / 1024.0f) + 1e-6f); bf16_t* rowp = U + (size_t)row * 4096 + col0;
; #pragma unroll
;                 for (int bj = 0; bj < 2; ++bj) { const f32x4 v0 = acc[ai][bj][m][0], v1 = acc[ai][bj][m][1];
;                     float f[8] = {v0[0], v0[1], v0[2], v0[3], v1[0], v1[1], v1[2], v1[3]};
; #pragma unroll
;                     for (int e = 0; e < 8; ++e) { const float r = fmaxf(f[e] * rs, 0.f); f[e] = r * r; }
;                     *(u32x4*)(rowp + bj * HALF) = pack8(f); } }
	global_store_dwordx4 v151, v[88:91], s[36:37]
	s_waitcnt lgkmcnt(4)
	global_store_dwordx4 v151, v[80:83], s[36:37] offset:256
	v_add_u32_e32 v151, 0x20000, v151
	s_waitcnt lgkmcnt(2)
	global_store_dwordx4 v151, v[72:75], s[36:37]
	s_waitcnt lgkmcnt(0)
	global_store_dwordx4 v151, v[64:67], s[36:37] offset:256
	v_pk_mul_f32 v[60:61], v[60:61], v[236:237] op_sel_hi:[1,0]
	v_pk_mul_f32 v[62:63], v[62:63], v[236:237] op_sel_hi:[1,0]
	v_pk_mul_f32 v[56:57], v[56:57], v[236:237] op_sel_hi:[1,0]
	v_pk_mul_f32 v[58:59], v[58:59], v[236:237] op_sel_hi:[1,0]
	v_max_f32_e32 v60, 0, v60
	v_max_f32_e32 v61, 0, v61
	v_max_f32_e32 v62, 0, v62
	v_max_f32_e32 v63, 0, v63
	v_max_f32_e32 v56, 0, v56
	v_max_f32_e32 v57, 0, v57
	v_max_f32_e32 v58, 0, v58
	v_max_f32_e32 v59, 0, v59
	v_pk_mul_f32 v[60:61], v[60:61], v[60:61]
	v_pk_mul_f32 v[62:63], v[62:63], v[62:63]
	v_pk_mul_f32 v[56:57], v[56:57], v[56:57]
	v_pk_mul_f32 v[58:59], v[58:59], v[58:59]
	v_cvt_pk_bf16_f32 v60, v60, v61
	v_cvt_pk_bf16_f32 v61, v62, v63
	v_cvt_pk_bf16_f32 v62, v56, v57
	v_cvt_pk_bf16_f32 v63, v58, v59
	ds_write_b128 v244, v[60:63]
	ds_read_b128 v[56:59], v245
	v_pk_mul_f32 v[52:53], v[52:53], v[236:237] op_sel_hi:[1,0]
	v_pk_mul_f32 v[54:55], v[54:55], v[236:237] op_sel_hi:[1,0]
	v_pk_mul_f32 v[48:49], v[48:49], v[236:237] op_sel_hi:[1,0]
	v_pk_mul_f32 v[50:51], v[50:51], v[236:237] op_sel_hi:[1,0]
	v_max_f32_e32 v52, 0, v52
	v_max_f32_e32 v53, 0, v53
	v_max_f32_e32 v54, 0, v54
	v_max_f32_e32 v55, 0, v55
	v_max_f32_e32 v48, 0, v48
	v_max_f32_e32 v49, 0, v49
	v_max_f32_e32 v50, 0, v50
	v_max_f32_e32 v51, 0, v51
	v_pk_mul_f32 v[52:53], v[52:53], v[52:53]
	v_pk_mul_f32 v[54:55], v[54:55], v[54:55]
	v_pk_mul_f32 v[48:49], v[48:49], v[48:49]
	v_pk_mul_f32 v[50:51], v[50:51], v[50:51]
	v_cvt_pk_bf16_f32 v52, v52, v53
	v_cvt_pk_bf16_f32 v53, v54, v55
	v_cvt_pk_bf16_f32 v54, v48, v49
	v_cvt_pk_bf16_f32 v55, v50, v51
	ds_write_b128 v244, v[52:55]
	ds_read_b128 v[48:51], v245
	v_pk_mul_f32 v[44:45], v[44:45], v[238:239] op_sel_hi:[1,0]
	v_pk_mul_f32 v[46:47], v[46:47], v[238:239] op_sel_hi:[1,0]
	v_pk_mul_f32 v[40:41], v[40:41], v[238:239] op_sel_hi:[1,0]
	v_pk_mul_f32 v[42:43], v[42:43], v[238:239] op_sel_hi:[1,0]
	v_max_f32_e32 v44, 0, v44
	v_max_f32_e32 v45, 0, v45
	v_max_f32_e32 v46, 0, v46
	v_max_f32_e32 v47, 0, v47
	v_max_f32_e32 v40, 0, v40
	v_max_f32_e32 v41, 0, v41
	v_max_f32_e32 v42, 0, v42
	v_max_f32_e32 v43, 0, v43
	v_pk_mul_f32 v[44:45], v[44:45], v[44:45]
	v_pk_mul_f32 v[46:47], v[46:47], v[46:47]
	v_pk_mul_f32 v[40:41], v[40:41], v[40:41]
	v_pk_mul_f32 v[42:43], v[42:43], v[42:43]
	v_cvt_pk_bf16_f32 v44, v44, v45
	v_cvt_pk_bf16_f32 v45, v46, v47
	v_cvt_pk_bf16_f32 v46, v40, v41
	v_cvt_pk_bf16_f32 v47, v42, v43
	ds_write_b128 v244, v[44:47]
	ds_read_b128 v[40:43], v245
	v_pk_mul_f32 v[36:37], v[36:37], v[238:239] op_sel_hi:[1,0]
	v_pk_mul_f32 v[38:39], v[38:39], v[238:239] op_sel_hi:[1,0]
	v_pk_mul_f32 v[32:33], v[32:33], v[238:239] op_sel_hi:[1,0]
	v_pk_mul_f32 v[34:35], v[34:35], v[238:239] op_sel_hi:[1,0]
	v_max_f32_e32 v36, 0, v36
	v_max_f32_e32 v37, 0, v37
	v_max_f32_e32 v38, 0, v38
	v_max_f32_e32 v39, 0, v39
	v_max_f32_e32 v32, 0, v32
	v_max_f32_e32 v33, 0, v33
	v_max_f32_e32 v34, 0, v34
	v_max_f32_e32 v35, 0, v35
	v_pk_mul_f32 v[36:37], v[36:37], v[36:37]
	v_pk_mul_f32 v[38:39], v[38:39], v[38:39]
	v_pk_mul_f32 v[32:33], v[32:33], v[32:33]
	v_pk_mul_f32 v[34:35], v[34:35], v[34:35]
	v_cvt_pk_bf16_f32 v36, v36, v37
	v_cvt_pk_bf16_f32 v37, v38, v39
	v_cvt_pk_bf16_f32 v38, v32, v33
	v_cvt_pk_bf16_f32 v39, v34, v35
	ds_write_b128 v244, v[36:39]
	ds_read_b128 v[32:35], v245
	v_add_u32_e32 v151, 0xa0000, v151
	s_waitcnt lgkmcnt(6)
	global_store_dwordx4 v151, v[56:59], s[36:37]
	s_waitcnt lgkmcnt(4)
	global_store_dwordx4 v151, v[48:51], s[36:37] offset:256
	v_add_u32_e32 v151, 0x20000, v151
	s_waitcnt lgkmcnt(2)
; __device__ __forceinline__ u32x4 pack8(const float (&f)[8]) { u32x4 w; w.x = cvt_pk_bf16(f[0], f[1]); w.y = cvt_pk_bf16(f[2], f[3]); w.z = cvt_pk_bf16(f[4], f[5]); w.w = cvt_pk_bf16(f[6], f[7]); return w; }
;     __device__ __forceinline__ void operator()(const f32x4 (&acc)[2][2][4][2], const Unit& u, int wr, int wc, int fr, int fq) const {
;         const int row0 = u.pm * BM + wr * 64 + fr, col0 = u.pn * BM + wc * 32 + 8 * fq;
; #pragma unroll
;         for (int ai = 0; ai < 2; ++ai)
; #pragma unroll
;             for (int m = 0; m < 4; ++m) { const int row = row0 + ai * HALF + m * 16; const float rs = __builtin_amdgcn_rsqf(ssq[row] * (1.0f / 1024.0f) + 1e-6f); bf16_t* rowp = U + (size_t)row * 4096 + col0;
; #pragma unroll
;                 for (int bj = 0; bj < 2; ++bj) { const f32x4 v0 = acc[ai][bj][m][0], v1 = acc[ai][bj][m][1];
;                     float f[8] = {v0[0], v0[1], v0[2], v0[3], v1[0], v1[1], v1[2], v1[3]};
; #pragma unroll
;                     for (int e = 0; e < 8; ++e) { const float r = fmaxf(f[e] * rs, 0.f); f[e] = r * r; }
;                     *(u32x4*)(rowp + bj * HALF) = pack8(f); } }
	global_store_dwordx4 v151, v[40:43], s[36:37]
	s_waitcnt lgkmcnt(0)
	global_store_dwordx4 v151, v[32:35], s[36:37] offset:256
	v_pk_mul_f32 v[28:29], v[28:29], v[240:241] op_sel_hi:[1,0]
	v_pk_mul_f32 v[30:31], v[30:31], v[240:241] op_sel_hi:[1,0]
	v_pk_mul_f32 v[24:25], v[24:25], v[240:241] op_sel_hi:[1,0]
	v_pk_mul_f32 v[26:27], v[26:27], v[240:241] op_sel_hi:[1,0]
	v_max_f32_e32 v28, 0, v28
	v_max_f32_e32 v29, 0, v29
	v_max_f32_e32 v30, 0, v30
	v_max_f32_e32 v31, 0, v31
	v_max_f32_e32 v24, 0, v24
	v_max_f32_e32 v25, 0, v25
	v_max_f32_e32 v26, 0, v26
	v_max_f32_e32 v27, 0, v27
	v_pk_mul_f32 v[28:29], v[28:29], v[28:29]
	v_pk_mul_f32 v[30:31], v[30:31], v[30:31]
	v_pk_mul_f32 v[24:25], v[24:25], v[24:25]
	v_pk_mul_f32 v[26:27], v[26:27], v[26:27]
	v_cvt_pk_bf16_f32 v28, v28, v29
	v_cvt_pk_bf16_f32 v29, v30, v31
	v_cvt_pk_bf16_f32 v30, v24, v25
	v_cvt_pk_bf16_f32 v31, v26, v27
	ds_write_b128 v244, v[28:31]
	ds_read_b128 v[24:27], v245
	v_pk_mul_f32 v[20:21], v[20:21], v[240:241] op_sel_hi:[1,0]
	v_pk_mul_f32 v[22:23], v[22:23], v[240:241] op_sel_hi:[1,0]
	v_pk_mul_f32 v[16:17], v[16:17], v[240:241] op_sel_hi:[1,0]
	v_pk_mul_f32 v[18:19], v[18:19], v[240:241] op_sel_hi:[1,0]
	v_max_f32_e32 v20, 0, v20
	v_max_f32_e32 v21, 0, v21
	v_max_f32_e32 v22, 0, v22
	v_max_f32_e32 v23, 0, v23
	v_max_f32_e32 v16, 0, v16
	v_max_f32_e32 v17, 0, v17
	v_max_f32_e32 v18, 0, v18
	v_max_f32_e32 v19, 0, v19
	v_pk_mul_f32 v[20:21], v[20:21], v[20:21]
	v_pk_mul_f32 v[22:23], v[22:23], v[22:23]
	v_pk_mul_f32 v[16:17], v[16:17], v[16:17]
	v_pk_mul_f32 v[18:19], v[18:19], v[18:19]
	v_cvt_pk_bf16_f32 v20, v20, v21
	v_cvt_pk_bf16_f32 v21, v22, v23
	v_cvt_pk_bf16_f32 v22, v16, v17
	v_cvt_pk_bf16_f32 v23, v18, v19
	ds_write_b128 v244, v[20:23]
	ds_read_b128 v[16:19], v245
	v_pk_mul_f32 v[12:13], v[12:13], v[242:243] op_sel_hi:[1,0]
	v_pk_mul_f32 v[14:15], v[14:15], v[242:243] op_sel_hi:[1,0]
	v_pk_mul_f32 v[8:9], v[8:9], v[242:243] op_sel_hi:[1,0]
	v_pk_mul_f32 v[10:11], v[10:11], v[242:243] op_sel_hi:[1,0]
	v_max_f32_e32 v12, 0, v12
	v_max_f32_e32 v13, 0, v13
	v_max_f32_e32 v14, 0, v14
	v_max_f32_e32 v15, 0, v15
	v_max_f32_e32 v8, 0, v8
	v_max_f32_e32 v9, 0, v9
	v_max_f32_e32 v10, 0, v10
	v_max_f32_e32 v11, 0, v11
	v_pk_mul_f32 v[12:13], v[12:13], v[12:13]
	v_pk_mul_f32 v[14:15], v[14:15], v[14:15]
	v_pk_mul_f32 v[8:9], v[8:9], v[8:9]
	v_pk_mul_f32 v[10:11], v[10:11], v[10:11]
	v_cvt_pk_bf16_f32 v12, v12, v13
	v_cvt_pk_bf16_f32 v13, v14, v15
	v_cvt_pk_bf16_f32 v14, v8, v9
	v_cvt_pk_bf16_f32 v15, v10, v11
	ds_write_b128 v244, v[12:15]
	ds_read_b128 v[8:11], v245
	v_pk_mul_f32 v[4:5], v[4:5], v[242:243] op_sel_hi:[1,0]
	v_pk_mul_f32 v[6:7], v[6:7], v[242:243] op_sel_hi:[1,0]
	v_pk_mul_f32 v[0:1], v[0:1], v[242:243] op_sel_hi:[1,0]
	v_pk_mul_f32 v[2:3], v[2:3], v[242:243] op_sel_hi:[1,0]
	v_max_f32_e32 v4, 0, v4
	v_max_f32_e32 v5, 0, v5
	v_max_f32_e32 v6, 0, v6
	v_max_f32_e32 v7, 0, v7
	v_max_f32_e32 v0, 0, v0
	v_max_f32_e32 v1, 0, v1
	v_max_f32_e32 v2, 0, v2
	v_max_f32_e32 v3, 0, v3
	v_pk_mul_f32 v[4:5], v[4:5], v[4:5]
	v_pk_mul_f32 v[6:7], v[6:7], v[6:7]
	v_pk_mul_f32 v[0:1], v[0:1], v[0:1]
	v_pk_mul_f32 v[2:3], v[2:3], v[2:3]
	v_cvt_pk_bf16_f32 v4, v4, v5
	v_cvt_pk_bf16_f32 v5, v6, v7
	v_cvt_pk_bf16_f32 v6, v0, v1
	v_cvt_pk_bf16_f32 v7, v2, v3
	ds_write_b128 v244, v[4:7]
	ds_read_b128 v[0:3], v245
	v_add_u32_e32 v151, 0x20000, v151
	s_waitcnt lgkmcnt(6)
	global_store_dwordx4 v151, v[24:27], s[36:37]
	s_waitcnt lgkmcnt(4)
	global_store_dwordx4 v151, v[16:19], s[36:37] offset:256
	v_add_u32_e32 v151, 0x20000, v151
	s_waitcnt lgkmcnt(2)
	global_store_dwordx4 v151, v[8:11], s[36:37]
	s_waitcnt lgkmcnt(0)
	global_store_dwordx4 v151, v[0:3], s[36:37] offset:256
	s_andn2_b64 vcc, exec, s[4:5]
	s_mov_b64 s[4:5], -1
	s_cbranch_vccnz .LBB0_729
	s_andn2_b64 vcc, exec, s[6:7]
	s_cbranch_vccnz .LBB0_728
	s_barrier
	s_branch .LBB0_728
